# phase 5 rebuilt on phase 1's 128x128 32x32x16 bf16 k-loop (1056 tiles), swapped MFMA operand order so the f32 residual epilogue is fully coalesced
# speedup vs baseline: 1.0202x; 1.0129x over previous
; template <class Epi>
; DI void gemm_phase(const u16* __restrict__ A, const u16* __restrict__ B, int mtiles, int ntiles, char* lds, const Epi& epi) {
;     ...
;     int m0, n0; TILE_MN(tile, m0, n0);
;     {
;         const int lane = threadIdx.x & 63, wave = __builtin_amdgcn_readfirstlane(threadIdx.x >> 6);
;         unsigned soff[4];
; #pragma unroll
;         for (int i = 0; i < 4; ++i) { const int row = 8 * (i * 4 + wave) + (lane >> 3); const int ch = (lane & 7) ^ ((row >> 1) & 7); soff[i] = (unsigned)(row * 1024 + ch * 8); }
;         GSTAGE(0, 0, A + (size_t)m0 * 1024, B + (size_t)n0 * 1024);
;     }
;     for (;;) {
;         int tid = threadIdx.x; asm volatile("" : "+v"(tid));
;         const int lane = tid & 63, wave = __builtin_amdgcn_readfirstlane(tid >> 6); const int wn = wave >> 1, wm = wave & 1; const int r = lane & 31, h = lane >> 5;
;         f32x16 acc[2][2];
; #pragma unroll
;         for (int a = 0; a < 2; ++a)
; #pragma unroll
;             for (int b = 0; b < 2; ++b)
; #pragma unroll
;                 for (int e = 0; e < 16; ++e) acc[a][b][e] = 0.f;
;         unsigned soff[4];
; #pragma unroll
;         for (int i = 0; i < 4; ++i) { const int row = 8 * (i * 4 + wave) + (lane >> 3); const int ch = (lane & 7) ^ ((row >> 1) & 7); soff[i] = (unsigned)(row * 1024 + ch * 8); }
;         const u16* ga = A + (size_t)m0 * 1024; const u16* gb = B + (size_t)n0 * 1024;
;         __syncthreads();
;         for (int kt = 0; kt < 16; ++kt) {
;             if (kt + 1 < 16) GSTAGE((kt + 1) & 1, kt + 1, ga, gb);
;             const char* sa = lds + (kt & 1) * 32768; const char* sb = sa + 16384;
; DI void gemm_out(const Params& p, char* lds) {
;     const u16* __restrict__ A = (const u16*)(p.ws + W_XB); const u16* __restrict__ B = (const u16*)(p.ws + W_WOUTT);
;     const int ntile = 176 * 8;
;     const int vb = (blockIdx.x & 7) * (gridDim.x >> 3) + (blockIdx.x >> 3);
;     for (int tile = vb; tile < ntile; tile += gridDim.x) {
;         int tid = threadIdx.x; asm volatile("" : "+v"(tid));
;         const int lane = tid & 63, wave = __builtin_amdgcn_readfirstlane(tid >> 6); const int wn = wave >> 1, wm = wave & 1; const int q = lane & 15, g = lane >> 4;
;         const int mt = tile >> 3, nt = tile & 7; const int m0 = mt * 96, n0 = nt * 128;
.LBB0_575:
	s_or_b64 exec, exec, s[0:1]
	s_cmpk_gt_i32 s64, 0x57f
	s_waitcnt lgkmcnt(0)
	s_barrier
	s_cmpk_gt_i32 s64, 0x41f
	s_cbranch_scc1 .LBB0_578
	s_mov_b32 s33, s64
	v_readlane_b32 s95, v236, 8
	s_add_u32 s10, s54, 0x2940000
	s_addc_u32 s11, s55, 0
	v_writelane_b32 v236, s10, 9
	s_nop 1
	v_writelane_b32 v236, s11, 11
	s_lshr_b32 s82, s33, 3
	s_lshl_b32 s82, s82, 7
	s_and_b32 s0, s33, 7
	s_lshl_b32 s0, s0, 7
	v_mov_b32_e32 v75, 0
	v_readfirstlane_b32 s4, v0
	s_lshr_b32 s6, s4, 6
	v_bfe_u32 v2, v0, 3, 3
	s_ashr_i32 s83, s82, 31
	v_lshl_or_b32 v2, s6, 3, v2
	s_lshl_b64 s[4:5], s[82:83], 11
	v_lshrrev_b32_e32 v3, 1, v2
	s_add_u32 s4, s54, s4
	v_xor_b32_e32 v3, v3, v0
	s_addc_u32 s5, s55, s5
	s_ashr_i32 s1, s0, 31
	s_lshl_b32 s8, s6, 10
	s_lshl_b64 s[6:7], s[0:1], 11
	v_lshlrev_b32_e32 v3, 4, v3
	s_add_u32 s6, s10, s6
	v_and_b32_e32 v3, 0x70, v3
	v_add_u32_e32 v4, 32, v2
	s_addc_u32 s7, s11, s7
	v_lshl_or_b32 v74, v2, 11, v3
	s_add_i32 s1, s8, 0
	v_lshrrev_b32_e32 v5, 1, v4
	v_add_u32_e32 v6, 64, v2
	v_add_u32_e32 v8, 0x60, v2
	v_lshl_add_u64 v[2:3], s[4:5], 0, v[74:75]
	s_mov_b32 m0, s1
	v_xor_b32_e32 v5, v5, v0
	global_load_lds_dwordx4 v[2:3], off
	v_lshl_add_u64 v[2:3], s[6:7], 0, v[74:75]
	s_add_i32 m0, s1, 0x4000
	v_lshrrev_b32_e32 v7, 1, v6
	global_load_lds_dwordx4 v[2:3], off
	v_lshlrev_b32_e32 v2, 4, v5
	v_and_b32_e32 v2, 0x70, v2
	v_lshl_or_b32 v74, v4, 11, v2
	v_lshl_add_u64 v[2:3], s[4:5], 0, v[74:75]
	s_add_i32 m0, s1, 0x1000
	v_xor_b32_e32 v7, v7, v0
	global_load_lds_dwordx4 v[2:3], off
	v_lshl_add_u64 v[2:3], s[6:7], 0, v[74:75]
	s_add_i32 m0, s1, 0x5000
	v_lshrrev_b32_e32 v9, 1, v8
	global_load_lds_dwordx4 v[2:3], off
	v_lshlrev_b32_e32 v2, 4, v7
	v_and_b32_e32 v2, 0x70, v2
	v_lshl_or_b32 v74, v6, 11, v2
	v_lshl_add_u64 v[2:3], s[4:5], 0, v[74:75]
	s_add_i32 m0, s1, 0x2000
	v_xor_b32_e32 v9, v9, v0
	global_load_lds_dwordx4 v[2:3], off
	v_lshl_add_u64 v[2:3], s[6:7], 0, v[74:75]
	s_add_i32 m0, s1, 0x6000
	global_load_lds_dwordx4 v[2:3], off
	v_lshlrev_b32_e32 v2, 4, v9
	v_and_b32_e32 v2, 0x70, v2
	v_lshl_or_b32 v74, v8, 11, v2
	v_lshl_add_u64 v[2:3], s[4:5], 0, v[74:75]
	s_add_i32 m0, s1, 0x3000
	global_load_lds_dwordx4 v[2:3], off
	v_lshl_add_u64 v[2:3], s[6:7], 0, v[74:75]
	s_add_i32 m0, s1, 0x7000
	global_load_lds_dwordx4 v[2:3], off
	s_mov_b32 s5, 0
	s_mov_b64 s[8:9], 0x80
	s_mov_b64 s[10:11], 0x100
	s_mov_b64 s[12:13], 0x180
	s_mov_b64 s[14:15], 0x200
	s_mov_b64 s[16:17], 0x280
	s_mov_b64 s[18:19], 0x300
	s_mov_b64 s[20:21], 0x380
	s_mov_b64 s[22:23], 0x400
	s_mov_b64 s[24:25], 0x480
	s_mov_b64 s[26:27], 0x500
	s_mov_b64 s[28:29], 0x580
	s_mov_b64 s[30:31], 0x600
	s_mov_b64 s[36:37], 0x680
	s_mov_b64 s[68:69], 0x700
	s_mov_b64 s[70:71], 0x780
.Lo_tile:
	v_mov_b32_e32 v18, v0
	s_ashr_i32 s83, s82, 31
	v_readfirstlane_b32 s1, v18
	s_ashr_i32 s7, s1, 6
	s_ashr_i32 s4, s1, 7
	s_and_b32 s6, s7, 1
	v_bfe_u32 v2, v18, 3, 3
	s_lshl_b64 s[38:39], s[82:83], 11
	v_lshl_or_b32 v2, s7, 3, v2
	s_add_u32 s38, s54, s38
	v_lshrrev_b32_e32 v3, 1, v2
	s_addc_u32 s39, s55, s39
	s_ashr_i32 s1, s0, 31
	v_xor_b32_e32 v3, v3, v18
	s_lshl_b64 s[50:51], s[0:1], 11
	v_readlane_b32 s1, v236, 9
	v_lshlrev_b32_e32 v2, 10, v2
	v_lshlrev_b32_e32 v3, 3, v3
	s_add_u32 s50, s1, s50
	v_readlane_b32 s1, v236, 11
	v_and_or_b32 v74, v3, 56, v2
	s_addc_u32 s51, s1, s51
	s_lshl_b32 s1, s7, 10
	v_lshlrev_b64 v[66:67], 1, v[74:75]
	s_add_i32 s1, s1, 0
	v_add_u32_e32 v2, 0x8000, v74
	v_bfe_u32 v93, v18, 5, 1
	v_lshrrev_b32_e32 v8, 1, v18
	v_mov_b32_e32 v3, v75
	v_lshl_add_u64 v[76:77], s[38:39], 0, v[66:67]
	s_add_i32 s86, s1, 0x8000
	v_bitop3_b32 v10, v93, v8, 7 bitop3:0x78
	v_lshl_add_u64 v[8:9], v[76:77], 0, s[8:9]
	s_mov_b32 m0, s86
	v_lshl_add_u64 v[78:79], s[50:51], 0, v[66:67]
	s_add_i32 s87, s1, 0xc000
	v_lshlrev_b64 v[68:69], 1, v[2:3]
	v_add_u32_e32 v4, 0x10000, v74
	s_waitcnt vmcnt(0) lgkmcnt(0)
	s_barrier
	v_mov_b32_e32 v5, v75
	global_load_lds_dwordx4 v[8:9], off
	v_lshl_add_u64 v[8:9], v[78:79], 0, s[8:9]
	s_mov_b32 m0, s87
	v_lshl_add_u64 v[80:81], s[38:39], 0, v[68:69]
	s_add_i32 s88, s1, 0x9000
	global_load_lds_dwordx4 v[8:9], off
	v_lshl_add_u64 v[2:3], v[80:81], 0, s[8:9]
	s_mov_b32 m0, s88
	v_lshl_add_u64 v[82:83], s[50:51], 0, v[68:69]
	s_add_i32 s89, s1, 0xd000
	v_lshlrev_b64 v[70:71], 1, v[4:5]
	v_add_u32_e32 v6, 0x18000, v74
	v_mov_b32_e32 v7, v75
	global_load_lds_dwordx4 v[2:3], off
	v_lshl_add_u64 v[2:3], v[82:83], 0, s[8:9]
	s_mov_b32 m0, s89
	v_lshl_add_u64 v[84:85], s[38:39], 0, v[70:71]
	s_add_i32 s91, s1, 0xa000
	global_load_lds_dwordx4 v[2:3], off
	v_lshl_add_u64 v[2:3], v[84:85], 0, s[8:9]
	s_mov_b32 m0, s91
	v_lshl_add_u64 v[86:87], s[50:51], 0, v[70:71]
	s_add_i32 s92, s1, 0xe000
	v_lshlrev_b64 v[72:73], 1, v[6:7]
	global_load_lds_dwordx4 v[2:3], off
	v_lshl_add_u64 v[2:3], v[86:87], 0, s[8:9]
	s_mov_b32 m0, s92
	v_lshl_add_u64 v[88:89], s[38:39], 0, v[72:73]
	s_add_i32 s93, s1, 0xb000
	v_and_b32_e32 v94, 31, v18
	global_load_lds_dwordx4 v[2:3], off
	v_lshl_add_u64 v[2:3], v[88:89], 0, s[8:9]
	s_mov_b32 m0, s93
	v_lshl_add_u64 v[90:91], s[50:51], 0, v[72:73]
	s_add_i32 s94, s1, 0xf000
	s_lshl_b32 s7, s4, 13
	v_lshlrev_b32_e32 v116, 7, v94
	global_load_lds_dwordx4 v[2:3], off
	v_lshl_add_u64 v[2:3], v[90:91], 0, s[8:9]
	s_mov_b32 m0, s94
	v_lshl_add_u32 v6, v10, 4, 0
	global_load_lds_dwordx4 v[2:3], off
	v_add3_u32 v74, v6, s7, v116
	ds_read_b128 v[2:5], v74 offset:16384
	s_lshl_b32 s38, s6, 13
	v_add3_u32 v96, v6, s38, v116
	v_bfe_u32 v117, v18, 1, 3
	ds_read_b128 v[6:9], v96
	ds_read_b128 v[10:13], v96 offset:4096
	ds_read_b128 v[14:17], v74 offset:20480
	v_bitop3_b32 v18, v93, v117, 2 bitop3:0x36
	v_lshl_add_u32 v18, v18, 4, 0
	v_add3_u32 v95, v18, s7, v116
	ds_read_b128 v[50:53], v95 offset:16384
	s_waitcnt lgkmcnt(0)
; template <class Epi>
; DI void gemm_phase(const u16* __restrict__ A, const u16* __restrict__ B, int mtiles, int ntiles, char* lds, const Epi& epi) {
;     ...
;         for (int kt = 0; kt < 16; ++kt) {
;             if (kt + 1 < 16) GSTAGE((kt + 1) & 1, kt + 1, ga, gb);
;             const char* sa = lds + (kt & 1) * 32768; const char* sb = sa + 16384;
; #pragma unroll
;             for (int ks = 0; ks < 4; ++ks) {
;                 bf16x8 fw[2], fx[2];
; #pragma unroll
;                 for (int ct = 0; ct < 2; ++ct) fw[ct] = *(const bf16x8*)(sb + swz(wn * 64 + ct * 32 + r, 2 * ks + h));
; #pragma unroll
;                 for (int tt = 0; tt < 2; ++tt) fx[tt] = *(const bf16x8*)(sa + swz(wm * 64 + tt * 32 + r, 2 * ks + h));
; #pragma unroll
;                 for (int ct = 0; ct < 2; ++ct)
; #pragma unroll
;                     for (int tt = 0; tt < 2; ++tt) acc[ct][tt] = __builtin_amdgcn_mfma_f32_32x32x16_bf16(fw[ct], fx[tt], acc[ct][tt], 0, 0, 0);
;             }
;             __syncthreads();
	v_mfma_f32_32x32x16_bf16 v[34:49], v[6:9], v[2:5], 0
	v_add3_u32 v97, v18, s38, v116
	ds_read_b128 v[98:101], v97
	ds_read_b128 v[102:105], v97 offset:4096
	ds_read_b128 v[106:109], v95 offset:20480
	s_mov_b32 m0, s1
	s_add_i32 s39, s1, 0x5000
	s_add_i32 s50, s1, 0x2000
	s_add_i32 s51, s1, 0x6000
	s_add_i32 s83, s1, 0x3000
	v_mfma_f32_32x32x16_bf16 v[18:33], v[10:13], v[2:5], 0
	s_add_i32 s90, s1, 0x7000
	s_add_i32 s33, s33, s95
	s_waitcnt lgkmcnt(0)
	v_mfma_f32_32x32x16_bf16 v[34:49], v[98:101], v[50:53], v[34:49]
	v_mfma_f32_32x32x16_bf16 v[18:33], v[102:105], v[50:53], v[18:33]
	v_mfma_f32_32x32x16_bf16 v[50:65], v[6:9], v[14:17], 0
	v_mfma_f32_32x32x16_bf16 v[2:17], v[10:13], v[14:17], 0
	v_mfma_f32_32x32x16_bf16 v[50:65], v[98:101], v[106:109], v[50:65]
	v_bitop3_b32 v98, v93, v117, 4 bitop3:0x36
	v_lshl_add_u32 v99, v98, 4, 0
	v_add3_u32 v98, v99, s7, v116
	v_add3_u32 v99, v99, s38, v116
	v_mfma_f32_32x32x16_bf16 v[2:17], v[102:105], v[106:109], v[2:17]
	ds_read_b128 v[100:103], v98 offset:16384
	ds_read_b128 v[104:107], v99
	ds_read_b128 v[108:111], v99 offset:4096
	ds_read_b128 v[112:115], v98 offset:20480
	s_waitcnt lgkmcnt(0)
	v_mfma_f32_32x32x16_bf16 v[34:49], v[104:107], v[100:103], v[34:49]
	v_mfma_f32_32x32x16_bf16 v[18:33], v[108:111], v[100:103], v[18:33]
	v_bitop3_b32 v100, v93, v117, 6 bitop3:0x36
	v_lshl_add_u32 v101, v100, 4, 0
	v_add3_u32 v100, v101, s7, v116
	v_add3_u32 v101, v101, s38, v116
	s_add_i32 s7, s1, 0x4000
	s_add_i32 s38, s1, 0x1000
	s_cmpk_gt_i32 s33, 0x41f
	v_mfma_f32_32x32x16_bf16 v[50:65], v[104:107], v[112:115], v[50:65]
	v_mfma_f32_32x32x16_bf16 v[2:17], v[108:111], v[112:115], v[2:17]
	ds_read_b128 v[238:241], v100 offset:16384
	ds_read_b128 v[242:245], v101
	ds_read_b128 v[246:249], v101 offset:4096
	ds_read_b128 v[250:253], v100 offset:20480
	s_waitcnt vmcnt(0) lgkmcnt(0)
	s_barrier
	ds_read_b128 v[102:105], v74 offset:49152
	ds_read_b128 v[106:109], v96 offset:32768
	ds_read_b128 v[110:113], v96 offset:36864
	ds_read_b128 v[114:117], v74 offset:53248
	v_mfma_f32_32x32x16_bf16 v[34:49], v[242:245], v[238:241], v[34:49]
	v_mfma_f32_32x32x16_bf16 v[18:33], v[246:249], v[238:241], v[18:33]
	v_lshl_add_u64 v[254:255], v[76:77], 0, s[10:11]
	global_load_lds_dwordx4 v[254:255], off
	v_lshl_add_u64 v[254:255], v[78:79], 0, s[10:11]
	s_mov_b32 m0, s7
	s_nop 0
	global_load_lds_dwordx4 v[254:255], off
	v_lshl_add_u64 v[254:255], v[80:81], 0, s[10:11]
	s_mov_b32 m0, s38
	v_mfma_f32_32x32x16_bf16 v[50:65], v[242:245], v[250:253], v[50:65]
	global_load_lds_dwordx4 v[254:255], off
	v_lshl_add_u64 v[254:255], v[82:83], 0, s[10:11]
	s_mov_b32 m0, s39
	s_nop 0
	global_load_lds_dwordx4 v[254:255], off
	v_lshl_add_u64 v[254:255], v[84:85], 0, s[10:11]
	s_mov_b32 m0, s50
	v_mfma_f32_32x32x16_bf16 v[2:17], v[246:249], v[250:253], v[2:17]
	global_load_lds_dwordx4 v[254:255], off
	v_lshl_add_u64 v[254:255], v[86:87], 0, s[10:11]
	s_mov_b32 m0, s51
	s_nop 0
	global_load_lds_dwordx4 v[254:255], off
	v_lshl_add_u64 v[254:255], v[88:89], 0, s[10:11]
	s_mov_b32 m0, s83
	s_nop 0
	global_load_lds_dwordx4 v[254:255], off
	v_lshl_add_u64 v[254:255], v[90:91], 0, s[10:11]
	s_mov_b32 m0, s90
	s_nop 0
	global_load_lds_dwordx4 v[254:255], off
	s_waitcnt lgkmcnt(0)
	ds_read_b128 v[238:241], v95 offset:49152
	ds_read_b128 v[242:245], v97 offset:32768
	ds_read_b128 v[246:249], v97 offset:36864
	ds_read_b128 v[250:253], v95 offset:53248
	v_mfma_f32_32x32x16_bf16 v[34:49], v[106:109], v[102:105], v[34:49]
	s_mov_b32 m0, s86
	v_mfma_f32_32x32x16_bf16 v[18:33], v[110:113], v[102:105], v[18:33]
	v_mfma_f32_32x32x16_bf16 v[50:65], v[106:109], v[114:117], v[50:65]
	v_mfma_f32_32x32x16_bf16 v[2:17], v[110:113], v[114:117], v[2:17]
	s_waitcnt lgkmcnt(0)
	ds_read_b128 v[102:105], v98 offset:49152
	ds_read_b128 v[106:109], v99 offset:32768
	ds_read_b128 v[110:113], v99 offset:36864
	ds_read_b128 v[114:117], v98 offset:53248
	v_mfma_f32_32x32x16_bf16 v[34:49], v[242:245], v[238:241], v[34:49]
	v_mfma_f32_32x32x16_bf16 v[18:33], v[246:249], v[238:241], v[18:33]
	v_mfma_f32_32x32x16_bf16 v[50:65], v[242:245], v[250:253], v[50:65]
	v_mfma_f32_32x32x16_bf16 v[2:17], v[246:249], v[250:253], v[2:17]
	s_waitcnt lgkmcnt(0)
	ds_read_b128 v[238:241], v100 offset:49152
	ds_read_b128 v[242:245], v101 offset:32768
	ds_read_b128 v[246:249], v101 offset:36864
	ds_read_b128 v[250:253], v100 offset:53248
	v_mfma_f32_32x32x16_bf16 v[34:49], v[106:109], v[102:105], v[34:49]
	v_mfma_f32_32x32x16_bf16 v[18:33], v[110:113], v[102:105], v[18:33]
	v_mfma_f32_32x32x16_bf16 v[50:65], v[106:109], v[114:117], v[50:65]
	v_mfma_f32_32x32x16_bf16 v[2:17], v[110:113], v[114:117], v[2:17]
	s_waitcnt vmcnt(0) lgkmcnt(0)
	s_barrier
; template <class Epi>
; DI void gemm_phase(const u16* __restrict__ A, const u16* __restrict__ B, int mtiles, int ntiles, char* lds, const Epi& epi) {
;     ...
;         for (int kt = 0; kt < 16; ++kt) {
;             if (kt + 1 < 16) GSTAGE((kt + 1) & 1, kt + 1, ga, gb);
;             const char* sa = lds + (kt & 1) * 32768; const char* sb = sa + 16384;
; #pragma unroll
;             for (int ks = 0; ks < 4; ++ks) {
;                 bf16x8 fw[2], fx[2];
; #pragma unroll
;                 for (int ct = 0; ct < 2; ++ct) fw[ct] = *(const bf16x8*)(sb + swz(wn * 64 + ct * 32 + r, 2 * ks + h));
; #pragma unroll
;                 for (int tt = 0; tt < 2; ++tt) fx[tt] = *(const bf16x8*)(sa + swz(wm * 64 + tt * 32 + r, 2 * ks + h));
; #pragma unroll
;                 for (int ct = 0; ct < 2; ++ct)
; #pragma unroll
;                     for (int tt = 0; tt < 2; ++tt) acc[ct][tt] = __builtin_amdgcn_mfma_f32_32x32x16_bf16(fw[ct], fx[tt], acc[ct][tt], 0, 0, 0);
;             }
;             __syncthreads();
	ds_read_b128 v[102:105], v74 offset:16384
	ds_read_b128 v[106:109], v96
	ds_read_b128 v[110:113], v96 offset:4096
	ds_read_b128 v[114:117], v74 offset:20480
	v_mfma_f32_32x32x16_bf16 v[34:49], v[242:245], v[238:241], v[34:49]
	v_mfma_f32_32x32x16_bf16 v[18:33], v[246:249], v[238:241], v[18:33]
	v_lshl_add_u64 v[254:255], v[76:77], 0, s[12:13]
	global_load_lds_dwordx4 v[254:255], off
	v_lshl_add_u64 v[254:255], v[78:79], 0, s[12:13]
	s_mov_b32 m0, s87
	s_nop 0
	global_load_lds_dwordx4 v[254:255], off
	v_lshl_add_u64 v[254:255], v[80:81], 0, s[12:13]
	s_mov_b32 m0, s88
	v_mfma_f32_32x32x16_bf16 v[50:65], v[242:245], v[250:253], v[50:65]
	global_load_lds_dwordx4 v[254:255], off
	v_lshl_add_u64 v[254:255], v[82:83], 0, s[12:13]
	s_mov_b32 m0, s89
	s_nop 0
	global_load_lds_dwordx4 v[254:255], off
	v_lshl_add_u64 v[254:255], v[84:85], 0, s[12:13]
	s_mov_b32 m0, s91
	v_mfma_f32_32x32x16_bf16 v[2:17], v[246:249], v[250:253], v[2:17]
	global_load_lds_dwordx4 v[254:255], off
	v_lshl_add_u64 v[254:255], v[86:87], 0, s[12:13]
	s_mov_b32 m0, s92
	s_nop 0
	global_load_lds_dwordx4 v[254:255], off
	v_lshl_add_u64 v[254:255], v[88:89], 0, s[12:13]
	s_mov_b32 m0, s93
	s_nop 0
	global_load_lds_dwordx4 v[254:255], off
	v_lshl_add_u64 v[254:255], v[90:91], 0, s[12:13]
	s_mov_b32 m0, s94
	s_nop 0
	global_load_lds_dwordx4 v[254:255], off
	s_waitcnt lgkmcnt(0)
	ds_read_b128 v[238:241], v95 offset:16384
	ds_read_b128 v[242:245], v97
	ds_read_b128 v[246:249], v97 offset:4096
	ds_read_b128 v[250:253], v95 offset:20480
	v_mfma_f32_32x32x16_bf16 v[34:49], v[106:109], v[102:105], v[34:49]
	s_mov_b32 m0, s1
	v_mfma_f32_32x32x16_bf16 v[18:33], v[110:113], v[102:105], v[18:33]
	v_mfma_f32_32x32x16_bf16 v[50:65], v[106:109], v[114:117], v[50:65]
	v_mfma_f32_32x32x16_bf16 v[2:17], v[110:113], v[114:117], v[2:17]
	s_waitcnt lgkmcnt(0)
	ds_read_b128 v[102:105], v98 offset:16384
	ds_read_b128 v[106:109], v99
	ds_read_b128 v[110:113], v99 offset:4096
	ds_read_b128 v[114:117], v98 offset:20480
	v_mfma_f32_32x32x16_bf16 v[34:49], v[242:245], v[238:241], v[34:49]
	v_mfma_f32_32x32x16_bf16 v[18:33], v[246:249], v[238:241], v[18:33]
	v_mfma_f32_32x32x16_bf16 v[50:65], v[242:245], v[250:253], v[50:65]
	v_mfma_f32_32x32x16_bf16 v[2:17], v[246:249], v[250:253], v[2:17]
	s_waitcnt lgkmcnt(0)
	ds_read_b128 v[238:241], v100 offset:16384
	ds_read_b128 v[242:245], v101
	ds_read_b128 v[246:249], v101 offset:4096
	ds_read_b128 v[250:253], v100 offset:20480
	v_mfma_f32_32x32x16_bf16 v[34:49], v[106:109], v[102:105], v[34:49]
	v_mfma_f32_32x32x16_bf16 v[18:33], v[110:113], v[102:105], v[18:33]
	v_mfma_f32_32x32x16_bf16 v[50:65], v[106:109], v[114:117], v[50:65]
	v_mfma_f32_32x32x16_bf16 v[2:17], v[110:113], v[114:117], v[2:17]
	s_waitcnt vmcnt(0) lgkmcnt(0)
	s_barrier
	ds_read_b128 v[102:105], v74 offset:49152
	ds_read_b128 v[106:109], v96 offset:32768
	ds_read_b128 v[110:113], v96 offset:36864
	ds_read_b128 v[114:117], v74 offset:53248
	v_mfma_f32_32x32x16_bf16 v[34:49], v[242:245], v[238:241], v[34:49]
	v_mfma_f32_32x32x16_bf16 v[18:33], v[246:249], v[238:241], v[18:33]
	v_lshl_add_u64 v[254:255], v[76:77], 0, s[14:15]
	global_load_lds_dwordx4 v[254:255], off
	v_lshl_add_u64 v[254:255], v[78:79], 0, s[14:15]
	s_mov_b32 m0, s7
	s_nop 0
	global_load_lds_dwordx4 v[254:255], off
	v_lshl_add_u64 v[254:255], v[80:81], 0, s[14:15]
	s_mov_b32 m0, s38
	v_mfma_f32_32x32x16_bf16 v[50:65], v[242:245], v[250:253], v[50:65]
	global_load_lds_dwordx4 v[254:255], off
	v_lshl_add_u64 v[254:255], v[82:83], 0, s[14:15]
	s_mov_b32 m0, s39
	s_nop 0
	global_load_lds_dwordx4 v[254:255], off
	v_lshl_add_u64 v[254:255], v[84:85], 0, s[14:15]
	s_mov_b32 m0, s50
	v_mfma_f32_32x32x16_bf16 v[2:17], v[246:249], v[250:253], v[2:17]
	global_load_lds_dwordx4 v[254:255], off
	v_lshl_add_u64 v[254:255], v[86:87], 0, s[14:15]
	s_mov_b32 m0, s51
	s_nop 0
	global_load_lds_dwordx4 v[254:255], off
	v_lshl_add_u64 v[254:255], v[88:89], 0, s[14:15]
	s_mov_b32 m0, s83
	s_nop 0
	global_load_lds_dwordx4 v[254:255], off
	v_lshl_add_u64 v[254:255], v[90:91], 0, s[14:15]
	s_mov_b32 m0, s90
	s_nop 0
	global_load_lds_dwordx4 v[254:255], off
	s_waitcnt lgkmcnt(0)
	ds_read_b128 v[238:241], v95 offset:49152
	ds_read_b128 v[242:245], v97 offset:32768
	ds_read_b128 v[246:249], v97 offset:36864
	ds_read_b128 v[250:253], v95 offset:53248
	v_mfma_f32_32x32x16_bf16 v[34:49], v[106:109], v[102:105], v[34:49]
	s_mov_b32 m0, s86
	v_mfma_f32_32x32x16_bf16 v[18:33], v[110:113], v[102:105], v[18:33]
	v_mfma_f32_32x32x16_bf16 v[50:65], v[106:109], v[114:117], v[50:65]
	v_mfma_f32_32x32x16_bf16 v[2:17], v[110:113], v[114:117], v[2:17]
	s_waitcnt lgkmcnt(0)
	ds_read_b128 v[102:105], v98 offset:49152
	ds_read_b128 v[106:109], v99 offset:32768
	ds_read_b128 v[110:113], v99 offset:36864
	ds_read_b128 v[114:117], v98 offset:53248
	v_mfma_f32_32x32x16_bf16 v[34:49], v[242:245], v[238:241], v[34:49]
	v_mfma_f32_32x32x16_bf16 v[18:33], v[246:249], v[238:241], v[18:33]
	v_mfma_f32_32x32x16_bf16 v[50:65], v[242:245], v[250:253], v[50:65]
	v_mfma_f32_32x32x16_bf16 v[2:17], v[246:249], v[250:253], v[2:17]
	s_waitcnt lgkmcnt(0)
	ds_read_b128 v[238:241], v100 offset:49152
	ds_read_b128 v[242:245], v101 offset:32768
	ds_read_b128 v[246:249], v101 offset:36864
	ds_read_b128 v[250:253], v100 offset:53248
	v_mfma_f32_32x32x16_bf16 v[34:49], v[106:109], v[102:105], v[34:49]
	v_mfma_f32_32x32x16_bf16 v[18:33], v[110:113], v[102:105], v[18:33]
	v_mfma_f32_32x32x16_bf16 v[50:65], v[106:109], v[114:117], v[50:65]
	v_mfma_f32_32x32x16_bf16 v[2:17], v[110:113], v[114:117], v[2:17]
	s_waitcnt vmcnt(0) lgkmcnt(0)
	s_barrier
; template <class Epi>
; DI void gemm_phase(const u16* __restrict__ A, const u16* __restrict__ B, int mtiles, int ntiles, char* lds, const Epi& epi) {
;     ...
;         for (int kt = 0; kt < 16; ++kt) {
;             if (kt + 1 < 16) GSTAGE((kt + 1) & 1, kt + 1, ga, gb);
;             const char* sa = lds + (kt & 1) * 32768; const char* sb = sa + 16384;
; #pragma unroll
;             for (int ks = 0; ks < 4; ++ks) {
;                 bf16x8 fw[2], fx[2];
; #pragma unroll
;                 for (int ct = 0; ct < 2; ++ct) fw[ct] = *(const bf16x8*)(sb + swz(wn * 64 + ct * 32 + r, 2 * ks + h));
; #pragma unroll
;                 for (int tt = 0; tt < 2; ++tt) fx[tt] = *(const bf16x8*)(sa + swz(wm * 64 + tt * 32 + r, 2 * ks + h));
; #pragma unroll
;                 for (int ct = 0; ct < 2; ++ct)
; #pragma unroll
;                     for (int tt = 0; tt < 2; ++tt) acc[ct][tt] = __builtin_amdgcn_mfma_f32_32x32x16_bf16(fw[ct], fx[tt], acc[ct][tt], 0, 0, 0);
;             }
;             __syncthreads();
	ds_read_b128 v[102:105], v74 offset:16384
	ds_read_b128 v[106:109], v96
	ds_read_b128 v[110:113], v96 offset:4096
	ds_read_b128 v[114:117], v74 offset:20480
	v_mfma_f32_32x32x16_bf16 v[34:49], v[242:245], v[238:241], v[34:49]
	v_mfma_f32_32x32x16_bf16 v[18:33], v[246:249], v[238:241], v[18:33]
	v_lshl_add_u64 v[254:255], v[76:77], 0, s[16:17]
	global_load_lds_dwordx4 v[254:255], off
	v_lshl_add_u64 v[254:255], v[78:79], 0, s[16:17]
	s_mov_b32 m0, s87
	s_nop 0
	global_load_lds_dwordx4 v[254:255], off
	v_lshl_add_u64 v[254:255], v[80:81], 0, s[16:17]
	s_mov_b32 m0, s88
	v_mfma_f32_32x32x16_bf16 v[50:65], v[242:245], v[250:253], v[50:65]
	global_load_lds_dwordx4 v[254:255], off
	v_lshl_add_u64 v[254:255], v[82:83], 0, s[16:17]
	s_mov_b32 m0, s89
	s_nop 0
	global_load_lds_dwordx4 v[254:255], off
	v_lshl_add_u64 v[254:255], v[84:85], 0, s[16:17]
	s_mov_b32 m0, s91
	v_mfma_f32_32x32x16_bf16 v[2:17], v[246:249], v[250:253], v[2:17]
	global_load_lds_dwordx4 v[254:255], off
	v_lshl_add_u64 v[254:255], v[86:87], 0, s[16:17]
	s_mov_b32 m0, s92
	s_nop 0
	global_load_lds_dwordx4 v[254:255], off
	v_lshl_add_u64 v[254:255], v[88:89], 0, s[16:17]
	s_mov_b32 m0, s93
	s_nop 0
	global_load_lds_dwordx4 v[254:255], off
	v_lshl_add_u64 v[254:255], v[90:91], 0, s[16:17]
	s_mov_b32 m0, s94
	s_nop 0
	global_load_lds_dwordx4 v[254:255], off
	s_waitcnt lgkmcnt(0)
	ds_read_b128 v[238:241], v95 offset:16384
	ds_read_b128 v[242:245], v97
	ds_read_b128 v[246:249], v97 offset:4096
	ds_read_b128 v[250:253], v95 offset:20480
	v_mfma_f32_32x32x16_bf16 v[34:49], v[106:109], v[102:105], v[34:49]
	s_mov_b32 m0, s1
	v_mfma_f32_32x32x16_bf16 v[18:33], v[110:113], v[102:105], v[18:33]
	v_mfma_f32_32x32x16_bf16 v[50:65], v[106:109], v[114:117], v[50:65]
	v_mfma_f32_32x32x16_bf16 v[2:17], v[110:113], v[114:117], v[2:17]
	s_waitcnt lgkmcnt(0)
	ds_read_b128 v[102:105], v98 offset:16384
	ds_read_b128 v[106:109], v99
	ds_read_b128 v[110:113], v99 offset:4096
	ds_read_b128 v[114:117], v98 offset:20480
	v_mfma_f32_32x32x16_bf16 v[34:49], v[242:245], v[238:241], v[34:49]
	v_mfma_f32_32x32x16_bf16 v[18:33], v[246:249], v[238:241], v[18:33]
	v_mfma_f32_32x32x16_bf16 v[50:65], v[242:245], v[250:253], v[50:65]
	v_mfma_f32_32x32x16_bf16 v[2:17], v[246:249], v[250:253], v[2:17]
	s_waitcnt lgkmcnt(0)
	ds_read_b128 v[238:241], v100 offset:16384
	ds_read_b128 v[242:245], v101
	ds_read_b128 v[246:249], v101 offset:4096
	ds_read_b128 v[250:253], v100 offset:20480
	v_mfma_f32_32x32x16_bf16 v[34:49], v[106:109], v[102:105], v[34:49]
	v_mfma_f32_32x32x16_bf16 v[18:33], v[110:113], v[102:105], v[18:33]
	v_mfma_f32_32x32x16_bf16 v[50:65], v[106:109], v[114:117], v[50:65]
	v_mfma_f32_32x32x16_bf16 v[2:17], v[110:113], v[114:117], v[2:17]
	s_waitcnt vmcnt(0) lgkmcnt(0)
	s_barrier
	ds_read_b128 v[102:105], v74 offset:49152
	ds_read_b128 v[106:109], v96 offset:32768
	ds_read_b128 v[110:113], v96 offset:36864
	ds_read_b128 v[114:117], v74 offset:53248
	v_mfma_f32_32x32x16_bf16 v[34:49], v[242:245], v[238:241], v[34:49]
	v_mfma_f32_32x32x16_bf16 v[18:33], v[246:249], v[238:241], v[18:33]
	v_lshl_add_u64 v[254:255], v[76:77], 0, s[18:19]
	global_load_lds_dwordx4 v[254:255], off
	v_lshl_add_u64 v[254:255], v[78:79], 0, s[18:19]
	s_mov_b32 m0, s7
	s_nop 0
	global_load_lds_dwordx4 v[254:255], off
	v_lshl_add_u64 v[254:255], v[80:81], 0, s[18:19]
	s_mov_b32 m0, s38
	v_mfma_f32_32x32x16_bf16 v[50:65], v[242:245], v[250:253], v[50:65]
	global_load_lds_dwordx4 v[254:255], off
	v_lshl_add_u64 v[254:255], v[82:83], 0, s[18:19]
	s_mov_b32 m0, s39
	s_nop 0
	global_load_lds_dwordx4 v[254:255], off
	v_lshl_add_u64 v[254:255], v[84:85], 0, s[18:19]
	s_mov_b32 m0, s50
	v_mfma_f32_32x32x16_bf16 v[2:17], v[246:249], v[250:253], v[2:17]
	global_load_lds_dwordx4 v[254:255], off
	v_lshl_add_u64 v[254:255], v[86:87], 0, s[18:19]
	s_mov_b32 m0, s51
	s_nop 0
	global_load_lds_dwordx4 v[254:255], off
	v_lshl_add_u64 v[254:255], v[88:89], 0, s[18:19]
	s_mov_b32 m0, s83
	s_nop 0
	global_load_lds_dwordx4 v[254:255], off
	v_lshl_add_u64 v[254:255], v[90:91], 0, s[18:19]
	s_mov_b32 m0, s90
	s_nop 0
	global_load_lds_dwordx4 v[254:255], off
	s_waitcnt lgkmcnt(0)
	ds_read_b128 v[238:241], v95 offset:49152
	ds_read_b128 v[242:245], v97 offset:32768
	ds_read_b128 v[246:249], v97 offset:36864
	ds_read_b128 v[250:253], v95 offset:53248
	v_mfma_f32_32x32x16_bf16 v[34:49], v[106:109], v[102:105], v[34:49]
	s_mov_b32 m0, s86
	v_mfma_f32_32x32x16_bf16 v[18:33], v[110:113], v[102:105], v[18:33]
	v_mfma_f32_32x32x16_bf16 v[50:65], v[106:109], v[114:117], v[50:65]
	v_mfma_f32_32x32x16_bf16 v[2:17], v[110:113], v[114:117], v[2:17]
	s_waitcnt lgkmcnt(0)
	ds_read_b128 v[102:105], v98 offset:49152
	ds_read_b128 v[106:109], v99 offset:32768
	ds_read_b128 v[110:113], v99 offset:36864
	ds_read_b128 v[114:117], v98 offset:53248
	v_mfma_f32_32x32x16_bf16 v[34:49], v[242:245], v[238:241], v[34:49]
	v_mfma_f32_32x32x16_bf16 v[18:33], v[246:249], v[238:241], v[18:33]
	v_mfma_f32_32x32x16_bf16 v[50:65], v[242:245], v[250:253], v[50:65]
	v_mfma_f32_32x32x16_bf16 v[2:17], v[246:249], v[250:253], v[2:17]
	s_waitcnt lgkmcnt(0)
	ds_read_b128 v[238:241], v100 offset:49152
	ds_read_b128 v[242:245], v101 offset:32768
	ds_read_b128 v[246:249], v101 offset:36864
	ds_read_b128 v[250:253], v100 offset:53248
	v_mfma_f32_32x32x16_bf16 v[34:49], v[106:109], v[102:105], v[34:49]
	v_mfma_f32_32x32x16_bf16 v[18:33], v[110:113], v[102:105], v[18:33]
	v_mfma_f32_32x32x16_bf16 v[50:65], v[106:109], v[114:117], v[50:65]
	v_mfma_f32_32x32x16_bf16 v[2:17], v[110:113], v[114:117], v[2:17]
	s_waitcnt vmcnt(0) lgkmcnt(0)
	s_barrier
; template <class Epi>
; DI void gemm_phase(const u16* __restrict__ A, const u16* __restrict__ B, int mtiles, int ntiles, char* lds, const Epi& epi) {
;     ...
;         for (int kt = 0; kt < 16; ++kt) {
;             if (kt + 1 < 16) GSTAGE((kt + 1) & 1, kt + 1, ga, gb);
;             const char* sa = lds + (kt & 1) * 32768; const char* sb = sa + 16384;
; #pragma unroll
;             for (int ks = 0; ks < 4; ++ks) {
;                 bf16x8 fw[2], fx[2];
; #pragma unroll
;                 for (int ct = 0; ct < 2; ++ct) fw[ct] = *(const bf16x8*)(sb + swz(wn * 64 + ct * 32 + r, 2 * ks + h));
; #pragma unroll
;                 for (int tt = 0; tt < 2; ++tt) fx[tt] = *(const bf16x8*)(sa + swz(wm * 64 + tt * 32 + r, 2 * ks + h));
; #pragma unroll
;                 for (int ct = 0; ct < 2; ++ct)
; #pragma unroll
;                     for (int tt = 0; tt < 2; ++tt) acc[ct][tt] = __builtin_amdgcn_mfma_f32_32x32x16_bf16(fw[ct], fx[tt], acc[ct][tt], 0, 0, 0);
;             }
;             __syncthreads();
	ds_read_b128 v[102:105], v74 offset:16384
	ds_read_b128 v[106:109], v96
	ds_read_b128 v[110:113], v96 offset:4096
	ds_read_b128 v[114:117], v74 offset:20480
	v_mfma_f32_32x32x16_bf16 v[34:49], v[242:245], v[238:241], v[34:49]
	v_mfma_f32_32x32x16_bf16 v[18:33], v[246:249], v[238:241], v[18:33]
	v_lshl_add_u64 v[254:255], v[76:77], 0, s[20:21]
	global_load_lds_dwordx4 v[254:255], off
	v_lshl_add_u64 v[254:255], v[78:79], 0, s[20:21]
	s_mov_b32 m0, s87
	s_nop 0
	global_load_lds_dwordx4 v[254:255], off
	v_lshl_add_u64 v[254:255], v[80:81], 0, s[20:21]
	s_mov_b32 m0, s88
	v_mfma_f32_32x32x16_bf16 v[50:65], v[242:245], v[250:253], v[50:65]
	global_load_lds_dwordx4 v[254:255], off
	v_lshl_add_u64 v[254:255], v[82:83], 0, s[20:21]
	s_mov_b32 m0, s89
	s_nop 0
	global_load_lds_dwordx4 v[254:255], off
	v_lshl_add_u64 v[254:255], v[84:85], 0, s[20:21]
	s_mov_b32 m0, s91
	v_mfma_f32_32x32x16_bf16 v[2:17], v[246:249], v[250:253], v[2:17]
	global_load_lds_dwordx4 v[254:255], off
	v_lshl_add_u64 v[254:255], v[86:87], 0, s[20:21]
	s_mov_b32 m0, s92
	s_nop 0
	global_load_lds_dwordx4 v[254:255], off
	v_lshl_add_u64 v[254:255], v[88:89], 0, s[20:21]
	s_mov_b32 m0, s93
	s_nop 0
	global_load_lds_dwordx4 v[254:255], off
	v_lshl_add_u64 v[254:255], v[90:91], 0, s[20:21]
	s_mov_b32 m0, s94
	s_nop 0
	global_load_lds_dwordx4 v[254:255], off
	s_waitcnt lgkmcnt(0)
	ds_read_b128 v[238:241], v95 offset:16384
	ds_read_b128 v[242:245], v97
	ds_read_b128 v[246:249], v97 offset:4096
	ds_read_b128 v[250:253], v95 offset:20480
	v_mfma_f32_32x32x16_bf16 v[34:49], v[106:109], v[102:105], v[34:49]
	s_mov_b32 m0, s1
	v_mfma_f32_32x32x16_bf16 v[18:33], v[110:113], v[102:105], v[18:33]
	v_mfma_f32_32x32x16_bf16 v[50:65], v[106:109], v[114:117], v[50:65]
	v_mfma_f32_32x32x16_bf16 v[2:17], v[110:113], v[114:117], v[2:17]
	s_waitcnt lgkmcnt(0)
	ds_read_b128 v[102:105], v98 offset:16384
	ds_read_b128 v[106:109], v99
	ds_read_b128 v[110:113], v99 offset:4096
	ds_read_b128 v[114:117], v98 offset:20480
	v_mfma_f32_32x32x16_bf16 v[34:49], v[242:245], v[238:241], v[34:49]
	v_mfma_f32_32x32x16_bf16 v[18:33], v[246:249], v[238:241], v[18:33]
	v_mfma_f32_32x32x16_bf16 v[50:65], v[242:245], v[250:253], v[50:65]
	v_mfma_f32_32x32x16_bf16 v[2:17], v[246:249], v[250:253], v[2:17]
	s_waitcnt lgkmcnt(0)
	ds_read_b128 v[238:241], v100 offset:16384
	ds_read_b128 v[242:245], v101
	ds_read_b128 v[246:249], v101 offset:4096
	ds_read_b128 v[250:253], v100 offset:20480
	v_mfma_f32_32x32x16_bf16 v[34:49], v[106:109], v[102:105], v[34:49]
	v_mfma_f32_32x32x16_bf16 v[18:33], v[110:113], v[102:105], v[18:33]
	v_mfma_f32_32x32x16_bf16 v[50:65], v[106:109], v[114:117], v[50:65]
	v_mfma_f32_32x32x16_bf16 v[2:17], v[110:113], v[114:117], v[2:17]
	s_waitcnt vmcnt(0) lgkmcnt(0)
	s_barrier
	ds_read_b128 v[102:105], v74 offset:49152
	ds_read_b128 v[106:109], v96 offset:32768
	ds_read_b128 v[110:113], v96 offset:36864
	ds_read_b128 v[114:117], v74 offset:53248
	v_mfma_f32_32x32x16_bf16 v[34:49], v[242:245], v[238:241], v[34:49]
	v_mfma_f32_32x32x16_bf16 v[18:33], v[246:249], v[238:241], v[18:33]
	v_lshl_add_u64 v[254:255], v[76:77], 0, s[22:23]
	global_load_lds_dwordx4 v[254:255], off
	v_lshl_add_u64 v[254:255], v[78:79], 0, s[22:23]
	s_mov_b32 m0, s7
	s_nop 0
	global_load_lds_dwordx4 v[254:255], off
	v_lshl_add_u64 v[254:255], v[80:81], 0, s[22:23]
	s_mov_b32 m0, s38
	v_mfma_f32_32x32x16_bf16 v[50:65], v[242:245], v[250:253], v[50:65]
	global_load_lds_dwordx4 v[254:255], off
	v_lshl_add_u64 v[254:255], v[82:83], 0, s[22:23]
	s_mov_b32 m0, s39
	s_nop 0
	global_load_lds_dwordx4 v[254:255], off
	v_lshl_add_u64 v[254:255], v[84:85], 0, s[22:23]
	s_mov_b32 m0, s50
	v_mfma_f32_32x32x16_bf16 v[2:17], v[246:249], v[250:253], v[2:17]
	global_load_lds_dwordx4 v[254:255], off
	v_lshl_add_u64 v[254:255], v[86:87], 0, s[22:23]
	s_mov_b32 m0, s51
	s_nop 0
	global_load_lds_dwordx4 v[254:255], off
	v_lshl_add_u64 v[254:255], v[88:89], 0, s[22:23]
	s_mov_b32 m0, s83
	s_nop 0
	global_load_lds_dwordx4 v[254:255], off
	v_lshl_add_u64 v[254:255], v[90:91], 0, s[22:23]
	s_mov_b32 m0, s90
	s_nop 0
	global_load_lds_dwordx4 v[254:255], off
	s_waitcnt lgkmcnt(0)
	ds_read_b128 v[238:241], v95 offset:49152
	ds_read_b128 v[242:245], v97 offset:32768
	ds_read_b128 v[246:249], v97 offset:36864
	ds_read_b128 v[250:253], v95 offset:53248
	v_mfma_f32_32x32x16_bf16 v[34:49], v[106:109], v[102:105], v[34:49]
	s_mov_b32 m0, s86
	v_mfma_f32_32x32x16_bf16 v[18:33], v[110:113], v[102:105], v[18:33]
	v_mfma_f32_32x32x16_bf16 v[50:65], v[106:109], v[114:117], v[50:65]
	v_mfma_f32_32x32x16_bf16 v[2:17], v[110:113], v[114:117], v[2:17]
	s_waitcnt lgkmcnt(0)
	ds_read_b128 v[102:105], v98 offset:49152
	ds_read_b128 v[106:109], v99 offset:32768
	ds_read_b128 v[110:113], v99 offset:36864
	ds_read_b128 v[114:117], v98 offset:53248
	v_mfma_f32_32x32x16_bf16 v[34:49], v[242:245], v[238:241], v[34:49]
	v_mfma_f32_32x32x16_bf16 v[18:33], v[246:249], v[238:241], v[18:33]
	v_mfma_f32_32x32x16_bf16 v[50:65], v[242:245], v[250:253], v[50:65]
	v_mfma_f32_32x32x16_bf16 v[2:17], v[246:249], v[250:253], v[2:17]
	s_waitcnt lgkmcnt(0)
	ds_read_b128 v[238:241], v100 offset:49152
	ds_read_b128 v[242:245], v101 offset:32768
	ds_read_b128 v[246:249], v101 offset:36864
	ds_read_b128 v[250:253], v100 offset:53248
	v_mfma_f32_32x32x16_bf16 v[34:49], v[106:109], v[102:105], v[34:49]
	v_mfma_f32_32x32x16_bf16 v[18:33], v[110:113], v[102:105], v[18:33]
	v_mfma_f32_32x32x16_bf16 v[50:65], v[106:109], v[114:117], v[50:65]
	v_mfma_f32_32x32x16_bf16 v[2:17], v[110:113], v[114:117], v[2:17]
	s_waitcnt vmcnt(0) lgkmcnt(0)
	s_barrier
; template <class Epi>
; DI void gemm_phase(const u16* __restrict__ A, const u16* __restrict__ B, int mtiles, int ntiles, char* lds, const Epi& epi) {
;     ...
;         for (int kt = 0; kt < 16; ++kt) {
;             if (kt + 1 < 16) GSTAGE((kt + 1) & 1, kt + 1, ga, gb);
;             const char* sa = lds + (kt & 1) * 32768; const char* sb = sa + 16384;
; #pragma unroll
;             for (int ks = 0; ks < 4; ++ks) {
;                 bf16x8 fw[2], fx[2];
; #pragma unroll
;                 for (int ct = 0; ct < 2; ++ct) fw[ct] = *(const bf16x8*)(sb + swz(wn * 64 + ct * 32 + r, 2 * ks + h));
; #pragma unroll
;                 for (int tt = 0; tt < 2; ++tt) fx[tt] = *(const bf16x8*)(sa + swz(wm * 64 + tt * 32 + r, 2 * ks + h));
; #pragma unroll
;                 for (int ct = 0; ct < 2; ++ct)
; #pragma unroll
;                     for (int tt = 0; tt < 2; ++tt) acc[ct][tt] = __builtin_amdgcn_mfma_f32_32x32x16_bf16(fw[ct], fx[tt], acc[ct][tt], 0, 0, 0);
;             }
;             __syncthreads();
	ds_read_b128 v[102:105], v74 offset:16384
	ds_read_b128 v[106:109], v96
	ds_read_b128 v[110:113], v96 offset:4096
	ds_read_b128 v[114:117], v74 offset:20480
	v_mfma_f32_32x32x16_bf16 v[34:49], v[242:245], v[238:241], v[34:49]
	v_mfma_f32_32x32x16_bf16 v[18:33], v[246:249], v[238:241], v[18:33]
	v_lshl_add_u64 v[254:255], v[76:77], 0, s[24:25]
	global_load_lds_dwordx4 v[254:255], off
	v_lshl_add_u64 v[254:255], v[78:79], 0, s[24:25]
	s_mov_b32 m0, s87
	s_nop 0
	global_load_lds_dwordx4 v[254:255], off
	v_lshl_add_u64 v[254:255], v[80:81], 0, s[24:25]
	s_mov_b32 m0, s88
	v_mfma_f32_32x32x16_bf16 v[50:65], v[242:245], v[250:253], v[50:65]
	global_load_lds_dwordx4 v[254:255], off
	v_lshl_add_u64 v[254:255], v[82:83], 0, s[24:25]
	s_mov_b32 m0, s89
	s_nop 0
	global_load_lds_dwordx4 v[254:255], off
	v_lshl_add_u64 v[254:255], v[84:85], 0, s[24:25]
	s_mov_b32 m0, s91
	v_mfma_f32_32x32x16_bf16 v[2:17], v[246:249], v[250:253], v[2:17]
	global_load_lds_dwordx4 v[254:255], off
	v_lshl_add_u64 v[254:255], v[86:87], 0, s[24:25]
	s_mov_b32 m0, s92
	s_nop 0
	global_load_lds_dwordx4 v[254:255], off
	v_lshl_add_u64 v[254:255], v[88:89], 0, s[24:25]
	s_mov_b32 m0, s93
	s_nop 0
	global_load_lds_dwordx4 v[254:255], off
	v_lshl_add_u64 v[254:255], v[90:91], 0, s[24:25]
	s_mov_b32 m0, s94
	s_nop 0
	global_load_lds_dwordx4 v[254:255], off
	s_waitcnt lgkmcnt(0)
	ds_read_b128 v[238:241], v95 offset:16384
	ds_read_b128 v[242:245], v97
	ds_read_b128 v[246:249], v97 offset:4096
	ds_read_b128 v[250:253], v95 offset:20480
	v_mfma_f32_32x32x16_bf16 v[34:49], v[106:109], v[102:105], v[34:49]
	s_mov_b32 m0, s1
	v_mfma_f32_32x32x16_bf16 v[18:33], v[110:113], v[102:105], v[18:33]
	v_mfma_f32_32x32x16_bf16 v[50:65], v[106:109], v[114:117], v[50:65]
	v_mfma_f32_32x32x16_bf16 v[2:17], v[110:113], v[114:117], v[2:17]
	s_waitcnt lgkmcnt(0)
	ds_read_b128 v[102:105], v98 offset:16384
	ds_read_b128 v[106:109], v99
	ds_read_b128 v[110:113], v99 offset:4096
	ds_read_b128 v[114:117], v98 offset:20480
	v_mfma_f32_32x32x16_bf16 v[34:49], v[242:245], v[238:241], v[34:49]
	v_mfma_f32_32x32x16_bf16 v[18:33], v[246:249], v[238:241], v[18:33]
	v_mfma_f32_32x32x16_bf16 v[50:65], v[242:245], v[250:253], v[50:65]
	v_mfma_f32_32x32x16_bf16 v[2:17], v[246:249], v[250:253], v[2:17]
	s_waitcnt lgkmcnt(0)
	ds_read_b128 v[238:241], v100 offset:16384
	ds_read_b128 v[242:245], v101
	ds_read_b128 v[246:249], v101 offset:4096
	ds_read_b128 v[250:253], v100 offset:20480
	v_mfma_f32_32x32x16_bf16 v[34:49], v[106:109], v[102:105], v[34:49]
	v_mfma_f32_32x32x16_bf16 v[18:33], v[110:113], v[102:105], v[18:33]
	v_mfma_f32_32x32x16_bf16 v[50:65], v[106:109], v[114:117], v[50:65]
	v_mfma_f32_32x32x16_bf16 v[2:17], v[110:113], v[114:117], v[2:17]
	s_waitcnt vmcnt(0) lgkmcnt(0)
	s_barrier
	ds_read_b128 v[102:105], v74 offset:49152
	ds_read_b128 v[106:109], v96 offset:32768
	ds_read_b128 v[110:113], v96 offset:36864
	ds_read_b128 v[114:117], v74 offset:53248
	v_mfma_f32_32x32x16_bf16 v[34:49], v[242:245], v[238:241], v[34:49]
	v_mfma_f32_32x32x16_bf16 v[18:33], v[246:249], v[238:241], v[18:33]
	v_lshl_add_u64 v[254:255], v[76:77], 0, s[26:27]
	global_load_lds_dwordx4 v[254:255], off
	v_lshl_add_u64 v[254:255], v[78:79], 0, s[26:27]
	s_mov_b32 m0, s7
	s_nop 0
	global_load_lds_dwordx4 v[254:255], off
	v_lshl_add_u64 v[254:255], v[80:81], 0, s[26:27]
	s_mov_b32 m0, s38
	v_mfma_f32_32x32x16_bf16 v[50:65], v[242:245], v[250:253], v[50:65]
	global_load_lds_dwordx4 v[254:255], off
	v_lshl_add_u64 v[254:255], v[82:83], 0, s[26:27]
	s_mov_b32 m0, s39
	s_nop 0
	global_load_lds_dwordx4 v[254:255], off
	v_lshl_add_u64 v[254:255], v[84:85], 0, s[26:27]
	s_mov_b32 m0, s50
	v_mfma_f32_32x32x16_bf16 v[2:17], v[246:249], v[250:253], v[2:17]
	global_load_lds_dwordx4 v[254:255], off
	v_lshl_add_u64 v[254:255], v[86:87], 0, s[26:27]
	s_mov_b32 m0, s51
	s_nop 0
	global_load_lds_dwordx4 v[254:255], off
	v_lshl_add_u64 v[254:255], v[88:89], 0, s[26:27]
	s_mov_b32 m0, s83
	s_nop 0
	global_load_lds_dwordx4 v[254:255], off
	v_lshl_add_u64 v[254:255], v[90:91], 0, s[26:27]
	s_mov_b32 m0, s90
	s_nop 0
	global_load_lds_dwordx4 v[254:255], off
	s_waitcnt lgkmcnt(0)
	ds_read_b128 v[238:241], v95 offset:49152
	ds_read_b128 v[242:245], v97 offset:32768
	ds_read_b128 v[246:249], v97 offset:36864
	ds_read_b128 v[250:253], v95 offset:53248
	v_mfma_f32_32x32x16_bf16 v[34:49], v[106:109], v[102:105], v[34:49]
	s_mov_b32 m0, s86
	v_mfma_f32_32x32x16_bf16 v[18:33], v[110:113], v[102:105], v[18:33]
	v_mfma_f32_32x32x16_bf16 v[50:65], v[106:109], v[114:117], v[50:65]
	v_mfma_f32_32x32x16_bf16 v[2:17], v[110:113], v[114:117], v[2:17]
	s_waitcnt lgkmcnt(0)
	ds_read_b128 v[102:105], v98 offset:49152
	ds_read_b128 v[106:109], v99 offset:32768
	ds_read_b128 v[110:113], v99 offset:36864
	ds_read_b128 v[114:117], v98 offset:53248
	v_mfma_f32_32x32x16_bf16 v[34:49], v[242:245], v[238:241], v[34:49]
	v_mfma_f32_32x32x16_bf16 v[18:33], v[246:249], v[238:241], v[18:33]
	v_mfma_f32_32x32x16_bf16 v[50:65], v[242:245], v[250:253], v[50:65]
	v_mfma_f32_32x32x16_bf16 v[2:17], v[246:249], v[250:253], v[2:17]
	s_waitcnt lgkmcnt(0)
	ds_read_b128 v[238:241], v100 offset:49152
	ds_read_b128 v[242:245], v101 offset:32768
	ds_read_b128 v[246:249], v101 offset:36864
	ds_read_b128 v[250:253], v100 offset:53248
	v_mfma_f32_32x32x16_bf16 v[34:49], v[106:109], v[102:105], v[34:49]
	v_mfma_f32_32x32x16_bf16 v[18:33], v[110:113], v[102:105], v[18:33]
	v_mfma_f32_32x32x16_bf16 v[50:65], v[106:109], v[114:117], v[50:65]
	v_mfma_f32_32x32x16_bf16 v[2:17], v[110:113], v[114:117], v[2:17]
	s_waitcnt vmcnt(0) lgkmcnt(0)
	s_barrier
; template <class Epi>
; DI void gemm_phase(const u16* __restrict__ A, const u16* __restrict__ B, int mtiles, int ntiles, char* lds, const Epi& epi) {
;     ...
;         for (int kt = 0; kt < 16; ++kt) {
;             if (kt + 1 < 16) GSTAGE((kt + 1) & 1, kt + 1, ga, gb);
;             const char* sa = lds + (kt & 1) * 32768; const char* sb = sa + 16384;
; #pragma unroll
;             for (int ks = 0; ks < 4; ++ks) {
;                 bf16x8 fw[2], fx[2];
; #pragma unroll
;                 for (int ct = 0; ct < 2; ++ct) fw[ct] = *(const bf16x8*)(sb + swz(wn * 64 + ct * 32 + r, 2 * ks + h));
; #pragma unroll
;                 for (int tt = 0; tt < 2; ++tt) fx[tt] = *(const bf16x8*)(sa + swz(wm * 64 + tt * 32 + r, 2 * ks + h));
; #pragma unroll
;                 for (int ct = 0; ct < 2; ++ct)
; #pragma unroll
;                     for (int tt = 0; tt < 2; ++tt) acc[ct][tt] = __builtin_amdgcn_mfma_f32_32x32x16_bf16(fw[ct], fx[tt], acc[ct][tt], 0, 0, 0);
;             }
;             __syncthreads();
	ds_read_b128 v[102:105], v74 offset:16384
	ds_read_b128 v[106:109], v96
	ds_read_b128 v[110:113], v96 offset:4096
	ds_read_b128 v[114:117], v74 offset:20480
	v_mfma_f32_32x32x16_bf16 v[34:49], v[242:245], v[238:241], v[34:49]
	v_mfma_f32_32x32x16_bf16 v[18:33], v[246:249], v[238:241], v[18:33]
	v_lshl_add_u64 v[254:255], v[76:77], 0, s[28:29]
	global_load_lds_dwordx4 v[254:255], off
	v_lshl_add_u64 v[254:255], v[78:79], 0, s[28:29]
	s_mov_b32 m0, s87
	s_nop 0
	global_load_lds_dwordx4 v[254:255], off
	v_lshl_add_u64 v[254:255], v[80:81], 0, s[28:29]
	s_mov_b32 m0, s88
	v_mfma_f32_32x32x16_bf16 v[50:65], v[242:245], v[250:253], v[50:65]
	global_load_lds_dwordx4 v[254:255], off
	v_lshl_add_u64 v[254:255], v[82:83], 0, s[28:29]
	s_mov_b32 m0, s89
	s_nop 0
	global_load_lds_dwordx4 v[254:255], off
	v_lshl_add_u64 v[254:255], v[84:85], 0, s[28:29]
	s_mov_b32 m0, s91
	v_mfma_f32_32x32x16_bf16 v[2:17], v[246:249], v[250:253], v[2:17]
	global_load_lds_dwordx4 v[254:255], off
	v_lshl_add_u64 v[254:255], v[86:87], 0, s[28:29]
	s_mov_b32 m0, s92
	s_nop 0
	global_load_lds_dwordx4 v[254:255], off
	v_lshl_add_u64 v[254:255], v[88:89], 0, s[28:29]
	s_mov_b32 m0, s93
	s_nop 0
	global_load_lds_dwordx4 v[254:255], off
	v_lshl_add_u64 v[254:255], v[90:91], 0, s[28:29]
	s_mov_b32 m0, s94
	s_nop 0
	global_load_lds_dwordx4 v[254:255], off
	s_waitcnt lgkmcnt(0)
	ds_read_b128 v[238:241], v95 offset:16384
	ds_read_b128 v[242:245], v97
	ds_read_b128 v[246:249], v97 offset:4096
	ds_read_b128 v[250:253], v95 offset:20480
	v_mfma_f32_32x32x16_bf16 v[34:49], v[106:109], v[102:105], v[34:49]
	s_mov_b32 m0, s1
	v_mfma_f32_32x32x16_bf16 v[18:33], v[110:113], v[102:105], v[18:33]
	v_mfma_f32_32x32x16_bf16 v[50:65], v[106:109], v[114:117], v[50:65]
	v_mfma_f32_32x32x16_bf16 v[2:17], v[110:113], v[114:117], v[2:17]
	s_waitcnt lgkmcnt(0)
	ds_read_b128 v[102:105], v98 offset:16384
	ds_read_b128 v[106:109], v99
	ds_read_b128 v[110:113], v99 offset:4096
	ds_read_b128 v[114:117], v98 offset:20480
	v_mfma_f32_32x32x16_bf16 v[34:49], v[242:245], v[238:241], v[34:49]
	v_mfma_f32_32x32x16_bf16 v[18:33], v[246:249], v[238:241], v[18:33]
	v_mfma_f32_32x32x16_bf16 v[50:65], v[242:245], v[250:253], v[50:65]
	v_mfma_f32_32x32x16_bf16 v[2:17], v[246:249], v[250:253], v[2:17]
	s_waitcnt lgkmcnt(0)
	ds_read_b128 v[238:241], v100 offset:16384
	ds_read_b128 v[242:245], v101
	ds_read_b128 v[246:249], v101 offset:4096
	ds_read_b128 v[250:253], v100 offset:20480
	v_mfma_f32_32x32x16_bf16 v[34:49], v[106:109], v[102:105], v[34:49]
	v_mfma_f32_32x32x16_bf16 v[18:33], v[110:113], v[102:105], v[18:33]
	v_mfma_f32_32x32x16_bf16 v[50:65], v[106:109], v[114:117], v[50:65]
	v_mfma_f32_32x32x16_bf16 v[2:17], v[110:113], v[114:117], v[2:17]
	s_waitcnt vmcnt(0) lgkmcnt(0)
	s_barrier
	ds_read_b128 v[102:105], v74 offset:49152
	ds_read_b128 v[106:109], v96 offset:32768
	ds_read_b128 v[110:113], v96 offset:36864
	ds_read_b128 v[114:117], v74 offset:53248
	v_mfma_f32_32x32x16_bf16 v[34:49], v[242:245], v[238:241], v[34:49]
	v_mfma_f32_32x32x16_bf16 v[18:33], v[246:249], v[238:241], v[18:33]
	v_lshl_add_u64 v[254:255], v[76:77], 0, s[30:31]
	global_load_lds_dwordx4 v[254:255], off
	v_lshl_add_u64 v[254:255], v[78:79], 0, s[30:31]
	s_mov_b32 m0, s7
	s_nop 0
	global_load_lds_dwordx4 v[254:255], off
	v_lshl_add_u64 v[254:255], v[80:81], 0, s[30:31]
	s_mov_b32 m0, s38
	v_mfma_f32_32x32x16_bf16 v[50:65], v[242:245], v[250:253], v[50:65]
	global_load_lds_dwordx4 v[254:255], off
	v_lshl_add_u64 v[254:255], v[82:83], 0, s[30:31]
	s_mov_b32 m0, s39
	s_nop 0
	global_load_lds_dwordx4 v[254:255], off
	v_lshl_add_u64 v[254:255], v[84:85], 0, s[30:31]
	s_mov_b32 m0, s50
	v_mfma_f32_32x32x16_bf16 v[2:17], v[246:249], v[250:253], v[2:17]
	global_load_lds_dwordx4 v[254:255], off
	v_lshl_add_u64 v[254:255], v[86:87], 0, s[30:31]
	s_mov_b32 m0, s51
	s_nop 0
	global_load_lds_dwordx4 v[254:255], off
	v_lshl_add_u64 v[254:255], v[88:89], 0, s[30:31]
	s_mov_b32 m0, s83
	s_nop 0
	global_load_lds_dwordx4 v[254:255], off
	v_lshl_add_u64 v[254:255], v[90:91], 0, s[30:31]
	s_mov_b32 m0, s90
	s_nop 0
	global_load_lds_dwordx4 v[254:255], off
	s_waitcnt lgkmcnt(0)
	ds_read_b128 v[238:241], v95 offset:49152
	ds_read_b128 v[242:245], v97 offset:32768
	ds_read_b128 v[246:249], v97 offset:36864
	ds_read_b128 v[250:253], v95 offset:53248
	v_mfma_f32_32x32x16_bf16 v[34:49], v[106:109], v[102:105], v[34:49]
	s_mov_b32 m0, s86
	v_mfma_f32_32x32x16_bf16 v[18:33], v[110:113], v[102:105], v[18:33]
	v_mfma_f32_32x32x16_bf16 v[50:65], v[106:109], v[114:117], v[50:65]
	v_mfma_f32_32x32x16_bf16 v[2:17], v[110:113], v[114:117], v[2:17]
	s_waitcnt lgkmcnt(0)
	ds_read_b128 v[102:105], v98 offset:49152
	ds_read_b128 v[106:109], v99 offset:32768
	ds_read_b128 v[110:113], v99 offset:36864
	ds_read_b128 v[114:117], v98 offset:53248
	v_mfma_f32_32x32x16_bf16 v[34:49], v[242:245], v[238:241], v[34:49]
	v_mfma_f32_32x32x16_bf16 v[18:33], v[246:249], v[238:241], v[18:33]
	v_mfma_f32_32x32x16_bf16 v[50:65], v[242:245], v[250:253], v[50:65]
	v_mfma_f32_32x32x16_bf16 v[2:17], v[246:249], v[250:253], v[2:17]
	s_waitcnt lgkmcnt(0)
	ds_read_b128 v[238:241], v100 offset:49152
	ds_read_b128 v[242:245], v101 offset:32768
	ds_read_b128 v[246:249], v101 offset:36864
	ds_read_b128 v[250:253], v100 offset:53248
	v_mfma_f32_32x32x16_bf16 v[34:49], v[106:109], v[102:105], v[34:49]
	v_mfma_f32_32x32x16_bf16 v[18:33], v[110:113], v[102:105], v[18:33]
	v_mfma_f32_32x32x16_bf16 v[50:65], v[106:109], v[114:117], v[50:65]
	v_mfma_f32_32x32x16_bf16 v[2:17], v[110:113], v[114:117], v[2:17]
	s_waitcnt vmcnt(0) lgkmcnt(0)
	s_barrier
; template <class Epi>
; DI void gemm_phase(const u16* __restrict__ A, const u16* __restrict__ B, int mtiles, int ntiles, char* lds, const Epi& epi) {
;     ...
;         for (int kt = 0; kt < 16; ++kt) {
;             if (kt + 1 < 16) GSTAGE((kt + 1) & 1, kt + 1, ga, gb);
;             const char* sa = lds + (kt & 1) * 32768; const char* sb = sa + 16384;
; #pragma unroll
;             for (int ks = 0; ks < 4; ++ks) {
;                 bf16x8 fw[2], fx[2];
; #pragma unroll
;                 for (int ct = 0; ct < 2; ++ct) fw[ct] = *(const bf16x8*)(sb + swz(wn * 64 + ct * 32 + r, 2 * ks + h));
; #pragma unroll
;                 for (int tt = 0; tt < 2; ++tt) fx[tt] = *(const bf16x8*)(sa + swz(wm * 64 + tt * 32 + r, 2 * ks + h));
; #pragma unroll
;                 for (int ct = 0; ct < 2; ++ct)
; #pragma unroll
;                     for (int tt = 0; tt < 2; ++tt) acc[ct][tt] = __builtin_amdgcn_mfma_f32_32x32x16_bf16(fw[ct], fx[tt], acc[ct][tt], 0, 0, 0);
;             }
;             __syncthreads();
	ds_read_b128 v[102:105], v74 offset:16384
	ds_read_b128 v[106:109], v96
	ds_read_b128 v[110:113], v96 offset:4096
	ds_read_b128 v[114:117], v74 offset:20480
	v_mfma_f32_32x32x16_bf16 v[34:49], v[242:245], v[238:241], v[34:49]
	v_mfma_f32_32x32x16_bf16 v[18:33], v[246:249], v[238:241], v[18:33]
	v_lshl_add_u64 v[254:255], v[76:77], 0, s[36:37]
	global_load_lds_dwordx4 v[254:255], off
	v_lshl_add_u64 v[254:255], v[78:79], 0, s[36:37]
	s_mov_b32 m0, s87
	s_nop 0
	global_load_lds_dwordx4 v[254:255], off
	v_lshl_add_u64 v[254:255], v[80:81], 0, s[36:37]
	s_mov_b32 m0, s88
	v_mfma_f32_32x32x16_bf16 v[50:65], v[242:245], v[250:253], v[50:65]
	global_load_lds_dwordx4 v[254:255], off
	v_lshl_add_u64 v[254:255], v[82:83], 0, s[36:37]
	s_mov_b32 m0, s89
	s_nop 0
	global_load_lds_dwordx4 v[254:255], off
	v_lshl_add_u64 v[254:255], v[84:85], 0, s[36:37]
	s_mov_b32 m0, s91
	v_mfma_f32_32x32x16_bf16 v[2:17], v[246:249], v[250:253], v[2:17]
	global_load_lds_dwordx4 v[254:255], off
	v_lshl_add_u64 v[254:255], v[86:87], 0, s[36:37]
	s_mov_b32 m0, s92
	s_nop 0
	global_load_lds_dwordx4 v[254:255], off
	v_lshl_add_u64 v[254:255], v[88:89], 0, s[36:37]
	s_mov_b32 m0, s93
	s_nop 0
	global_load_lds_dwordx4 v[254:255], off
	v_lshl_add_u64 v[254:255], v[90:91], 0, s[36:37]
	s_mov_b32 m0, s94
	s_nop 0
	global_load_lds_dwordx4 v[254:255], off
	s_waitcnt lgkmcnt(0)
	ds_read_b128 v[238:241], v95 offset:16384
	ds_read_b128 v[242:245], v97
	ds_read_b128 v[246:249], v97 offset:4096
	ds_read_b128 v[250:253], v95 offset:20480
	v_mfma_f32_32x32x16_bf16 v[34:49], v[106:109], v[102:105], v[34:49]
	s_mov_b32 m0, s1
	v_mfma_f32_32x32x16_bf16 v[18:33], v[110:113], v[102:105], v[18:33]
	v_mfma_f32_32x32x16_bf16 v[50:65], v[106:109], v[114:117], v[50:65]
	v_mfma_f32_32x32x16_bf16 v[2:17], v[110:113], v[114:117], v[2:17]
	s_waitcnt lgkmcnt(0)
	ds_read_b128 v[102:105], v98 offset:16384
	ds_read_b128 v[106:109], v99
	ds_read_b128 v[110:113], v99 offset:4096
	ds_read_b128 v[114:117], v98 offset:20480
	v_mfma_f32_32x32x16_bf16 v[34:49], v[242:245], v[238:241], v[34:49]
	v_mfma_f32_32x32x16_bf16 v[18:33], v[246:249], v[238:241], v[18:33]
	v_mfma_f32_32x32x16_bf16 v[50:65], v[242:245], v[250:253], v[50:65]
	v_mfma_f32_32x32x16_bf16 v[2:17], v[246:249], v[250:253], v[2:17]
	s_waitcnt lgkmcnt(0)
	ds_read_b128 v[238:241], v100 offset:16384
	ds_read_b128 v[242:245], v101
	ds_read_b128 v[246:249], v101 offset:4096
	ds_read_b128 v[250:253], v100 offset:20480
	v_mfma_f32_32x32x16_bf16 v[34:49], v[106:109], v[102:105], v[34:49]
	v_mfma_f32_32x32x16_bf16 v[18:33], v[110:113], v[102:105], v[18:33]
	v_mfma_f32_32x32x16_bf16 v[50:65], v[106:109], v[114:117], v[50:65]
	v_mfma_f32_32x32x16_bf16 v[2:17], v[110:113], v[114:117], v[2:17]
	s_waitcnt vmcnt(0) lgkmcnt(0)
	s_barrier
	ds_read_b128 v[102:105], v74 offset:49152
	ds_read_b128 v[106:109], v96 offset:32768
	ds_read_b128 v[110:113], v96 offset:36864
	ds_read_b128 v[114:117], v74 offset:53248
	v_mfma_f32_32x32x16_bf16 v[34:49], v[242:245], v[238:241], v[34:49]
	v_mfma_f32_32x32x16_bf16 v[18:33], v[246:249], v[238:241], v[18:33]
	v_lshl_add_u64 v[254:255], v[76:77], 0, s[68:69]
	global_load_lds_dwordx4 v[254:255], off
	v_lshl_add_u64 v[254:255], v[78:79], 0, s[68:69]
	s_mov_b32 m0, s7
	v_lshl_add_u64 v[76:77], v[76:77], 0, s[70:71]
	global_load_lds_dwordx4 v[254:255], off
	v_lshl_add_u64 v[254:255], v[80:81], 0, s[68:69]
	s_mov_b32 m0, s38
	v_mfma_f32_32x32x16_bf16 v[50:65], v[242:245], v[250:253], v[50:65]
	global_load_lds_dwordx4 v[254:255], off
	v_lshl_add_u64 v[254:255], v[82:83], 0, s[68:69]
	s_mov_b32 m0, s39
	s_nop 0
	global_load_lds_dwordx4 v[254:255], off
	v_lshl_add_u64 v[254:255], v[84:85], 0, s[68:69]
	s_mov_b32 m0, s50
	v_mfma_f32_32x32x16_bf16 v[2:17], v[246:249], v[250:253], v[2:17]
	global_load_lds_dwordx4 v[254:255], off
	v_lshl_add_u64 v[254:255], v[86:87], 0, s[68:69]
	s_mov_b32 m0, s51
	s_nop 0
	global_load_lds_dwordx4 v[254:255], off
	v_lshl_add_u64 v[254:255], v[88:89], 0, s[68:69]
	s_mov_b32 m0, s83
	s_nop 0
	global_load_lds_dwordx4 v[254:255], off
	v_lshl_add_u64 v[254:255], v[90:91], 0, s[68:69]
	s_mov_b32 m0, s90
	s_nop 0
	global_load_lds_dwordx4 v[254:255], off
	s_waitcnt lgkmcnt(0)
	ds_read_b128 v[238:241], v95 offset:49152
	ds_read_b128 v[242:245], v97 offset:32768
	ds_read_b128 v[246:249], v97 offset:36864
	ds_read_b128 v[250:253], v95 offset:53248
	v_mfma_f32_32x32x16_bf16 v[34:49], v[106:109], v[102:105], v[34:49]
	s_mov_b32 m0, s86
	s_mov_b32 s86, 0
	v_mfma_f32_32x32x16_bf16 v[18:33], v[110:113], v[102:105], v[18:33]
	v_mfma_f32_32x32x16_bf16 v[50:65], v[106:109], v[114:117], v[50:65]
	v_mfma_f32_32x32x16_bf16 v[2:17], v[110:113], v[114:117], v[2:17]
	s_waitcnt lgkmcnt(0)
	ds_read_b128 v[102:105], v98 offset:49152
	ds_read_b128 v[106:109], v99 offset:32768
	ds_read_b128 v[110:113], v99 offset:36864
	ds_read_b128 v[114:117], v98 offset:53248
	v_mfma_f32_32x32x16_bf16 v[34:49], v[242:245], v[238:241], v[34:49]
	v_mfma_f32_32x32x16_bf16 v[18:33], v[246:249], v[238:241], v[18:33]
	v_mfma_f32_32x32x16_bf16 v[50:65], v[242:245], v[250:253], v[50:65]
	v_mfma_f32_32x32x16_bf16 v[2:17], v[246:249], v[250:253], v[2:17]
	s_waitcnt lgkmcnt(0)
	ds_read_b128 v[238:241], v100 offset:49152
	ds_read_b128 v[242:245], v101 offset:32768
	ds_read_b128 v[246:249], v101 offset:36864
	ds_read_b128 v[250:253], v100 offset:53248
	v_mfma_f32_32x32x16_bf16 v[34:49], v[106:109], v[102:105], v[34:49]
	v_mfma_f32_32x32x16_bf16 v[18:33], v[110:113], v[102:105], v[18:33]
	v_mfma_f32_32x32x16_bf16 v[50:65], v[106:109], v[114:117], v[50:65]
	v_mfma_f32_32x32x16_bf16 v[2:17], v[110:113], v[114:117], v[2:17]
	s_waitcnt vmcnt(0) lgkmcnt(0)
	s_barrier
; #define TILE_MN(t, M0, N0) do { int pan_ = (t) / (mtiles * 8); if (pan_ >= npan) pan_ = npan - 1; const int pw_ = (pan_ == npan - 1) ? ntiles - 8 * pan_ : 8; const int loc_ = (t) - pan_ * mtiles * 8; \
;         M0 = (loc_ / pw_) * 128; N0 = (8 * pan_ + loc_ % pw_) * 128; } while (0)
; template <class Epi>
; DI void gemm_phase(const u16* __restrict__ A, const u16* __restrict__ B, int mtiles, int ntiles, char* lds, const Epi& epi) {
;     ...
;         const int nxt = tile + (int)gridDim.x; int m1 = 0, n1 = 0;
;         if (nxt < ntile) { TILE_MN(nxt, m1, n1); GSTAGE(0, 0, A + (size_t)m1 * 1024, B + (size_t)n1 * 1024); }
; DI void gemm_out(const Params& p, char* lds) {
;     ...
;         for (int kt = 0; kt < 16; ++kt) {
;             if (kt + 1 < 16) OSTAGE((kt + 1) & 1, kt + 1);
;             const char* sb = lds + (kt & 1) * 28672; const char* sa = sb + 16384;
; #pragma unroll
;             for (int ks = 0; ks < 2; ++ks) {
;                 bf16x8 fw[4], fx[3];
; #pragma unroll
;                 for (int ct = 0; ct < 4; ++ct) fw[ct] = *(const bf16x8*)(sb + swz(wn * 64 + ct * 16 + q, 4 * ks + g));
; #pragma unroll
;                 for (int tt = 0; tt < 3; ++tt) fx[tt] = *(const bf16x8*)(sa + swz(wm * 48 + tt * 16 + q, 4 * ks + g));
; #pragma unroll
;                 for (int ct = 0; ct < 4; ++ct)
; #pragma unroll
;                     for (int tt = 0; tt < 3; ++tt) acc[ct][tt] = __builtin_amdgcn_mfma_f32_16x16x32_bf16(fw[ct], fx[tt], acc[ct][tt], 0, 0, 0);
;             }
;             __syncthreads();
;         }
	global_load_lds_dwordx4 v[76:77], off
	v_lshl_add_u64 v[76:77], v[78:79], 0, s[70:71]
	s_mov_b32 m0, s87
	v_mfma_f32_32x32x16_bf16 v[34:49], v[242:245], v[238:241], v[34:49]
	global_load_lds_dwordx4 v[76:77], off
	v_lshl_add_u64 v[76:77], v[80:81], 0, s[70:71]
	s_mov_b32 m0, s88
	s_mov_b32 s88, 0
	global_load_lds_dwordx4 v[76:77], off
	v_lshl_add_u64 v[76:77], v[82:83], 0, s[70:71]
	s_mov_b32 m0, s89
	v_mfma_f32_32x32x16_bf16 v[18:33], v[246:249], v[238:241], v[18:33]
	global_load_lds_dwordx4 v[76:77], off
	v_lshl_add_u64 v[76:77], v[84:85], 0, s[70:71]
	s_mov_b32 m0, s91
	s_nop 0
	global_load_lds_dwordx4 v[76:77], off
	v_lshl_add_u64 v[76:77], v[86:87], 0, s[70:71]
	s_mov_b32 m0, s92
	v_mfma_f32_32x32x16_bf16 v[50:65], v[242:245], v[250:253], v[50:65]
	global_load_lds_dwordx4 v[76:77], off
	v_lshl_add_u64 v[76:77], v[88:89], 0, s[70:71]
	s_mov_b32 m0, s93
	s_nop 0
	global_load_lds_dwordx4 v[76:77], off
	v_lshl_add_u64 v[76:77], v[90:91], 0, s[70:71]
	s_mov_b32 m0, s94
	v_mfma_f32_32x32x16_bf16 v[2:17], v[246:249], v[250:253], v[2:17]
	global_load_lds_dwordx4 v[76:77], off
	ds_read_b128 v[76:79], v74 offset:16384
	ds_read_b128 v[80:83], v96
	ds_read_b128 v[84:87], v96 offset:4096
	ds_read_b128 v[88:91], v74 offset:20480
	s_waitcnt lgkmcnt(0)
	v_mfma_f32_32x32x16_bf16 v[34:49], v[80:83], v[76:79], v[34:49]
	v_mfma_f32_32x32x16_bf16 v[18:33], v[84:87], v[76:79], v[18:33]
	v_mfma_f32_32x32x16_bf16 v[50:65], v[80:83], v[88:91], v[50:65]
	v_mfma_f32_32x32x16_bf16 v[2:17], v[84:87], v[88:91], v[2:17]
	ds_read_b128 v[76:79], v95 offset:16384
	ds_read_b128 v[80:83], v97
	ds_read_b128 v[84:87], v97 offset:4096
	ds_read_b128 v[88:91], v95 offset:20480
	s_waitcnt lgkmcnt(0)
	v_mfma_f32_32x32x16_bf16 v[34:49], v[80:83], v[76:79], v[34:49]
	v_mfma_f32_32x32x16_bf16 v[18:33], v[84:87], v[76:79], v[18:33]
	v_mfma_f32_32x32x16_bf16 v[50:65], v[80:83], v[88:91], v[50:65]
	v_mfma_f32_32x32x16_bf16 v[2:17], v[84:87], v[88:91], v[2:17]
	ds_read_b128 v[76:79], v98 offset:16384
	ds_read_b128 v[80:83], v99
	ds_read_b128 v[84:87], v99 offset:4096
	ds_read_b128 v[88:91], v98 offset:20480
	s_waitcnt lgkmcnt(0)
	v_mfma_f32_32x32x16_bf16 v[34:49], v[80:83], v[76:79], v[34:49]
	v_mfma_f32_32x32x16_bf16 v[18:33], v[84:87], v[76:79], v[18:33]
	v_mfma_f32_32x32x16_bf16 v[50:65], v[80:83], v[88:91], v[50:65]
	v_mfma_f32_32x32x16_bf16 v[2:17], v[84:87], v[88:91], v[2:17]
	ds_read_b128 v[76:79], v100 offset:16384
	ds_read_b128 v[80:83], v101
	ds_read_b128 v[84:87], v101 offset:4096
	ds_read_b128 v[88:91], v100 offset:20480
	s_waitcnt vmcnt(0) lgkmcnt(0)
	s_barrier
	v_mfma_f32_32x32x16_bf16 v[34:49], v[80:83], v[76:79], v[34:49]
	v_mfma_f32_32x32x16_bf16 v[18:33], v[84:87], v[76:79], v[18:33]
	v_mfma_f32_32x32x16_bf16 v[50:65], v[80:83], v[88:91], v[50:65]
	v_mfma_f32_32x32x16_bf16 v[2:17], v[84:87], v[88:91], v[2:17]
	ds_read_b128 v[76:79], v96 offset:32768
	ds_read_b128 v[80:83], v96 offset:36864
	ds_read_b128 v[84:87], v74 offset:49152
	ds_read_b128 v[88:91], v74 offset:53248
	s_waitcnt lgkmcnt(1)
	v_mfma_f32_32x32x16_bf16 v[34:49], v[76:79], v[84:87], v[34:49]
	v_mfma_f32_32x32x16_bf16 v[18:33], v[80:83], v[84:87], v[18:33]
	s_waitcnt lgkmcnt(0)
	v_mfma_f32_32x32x16_bf16 v[50:65], v[76:79], v[88:91], v[50:65]
	v_mfma_f32_32x32x16_bf16 v[2:17], v[80:83], v[88:91], v[2:17]
	ds_read_b128 v[76:79], v95 offset:49152
	ds_read_b128 v[80:83], v97 offset:32768
	ds_read_b128 v[84:87], v97 offset:36864
	ds_read_b128 v[88:91], v95 offset:53248
	s_waitcnt lgkmcnt(2)
	v_mfma_f32_32x32x16_bf16 v[34:49], v[80:83], v[76:79], v[34:49]
	s_waitcnt lgkmcnt(1)
	v_mfma_f32_32x32x16_bf16 v[18:33], v[84:87], v[76:79], v[18:33]
	s_waitcnt lgkmcnt(0)
	v_mfma_f32_32x32x16_bf16 v[50:65], v[80:83], v[88:91], v[50:65]
	v_mfma_f32_32x32x16_bf16 v[2:17], v[84:87], v[88:91], v[2:17]
	ds_read_b128 v[76:79], v98 offset:49152
	ds_read_b128 v[80:83], v99 offset:32768
	ds_read_b128 v[84:87], v99 offset:36864
	ds_read_b128 v[88:91], v98 offset:53248
	s_waitcnt lgkmcnt(2)
	v_mfma_f32_32x32x16_bf16 v[34:49], v[80:83], v[76:79], v[34:49]
	s_waitcnt lgkmcnt(1)
	v_mfma_f32_32x32x16_bf16 v[18:33], v[84:87], v[76:79], v[18:33]
	s_waitcnt lgkmcnt(0)
	v_mfma_f32_32x32x16_bf16 v[50:65], v[80:83], v[88:91], v[50:65]
	v_mfma_f32_32x32x16_bf16 v[2:17], v[84:87], v[88:91], v[2:17]
	ds_read_b128 v[76:79], v100 offset:49152
	ds_read_b128 v[80:83], v101 offset:32768
	ds_read_b128 v[84:87], v101 offset:36864
	ds_read_b128 v[88:91], v100 offset:53248
	s_waitcnt lgkmcnt(0)
	s_barrier
	v_mfma_f32_32x32x16_bf16 v[34:49], v[80:83], v[76:79], v[34:49]
	v_mfma_f32_32x32x16_bf16 v[18:33], v[84:87], v[76:79], v[18:33]
	v_mfma_f32_32x32x16_bf16 v[50:65], v[80:83], v[88:91], v[50:65]
	v_mfma_f32_32x32x16_bf16 v[2:17], v[84:87], v[88:91], v[2:17]
	s_cbranch_scc1 .Lo_nonext
	s_mov_b32 m0, s1
	s_lshr_b32 s86, s33, 3
	s_lshl_b32 s86, s86, 7
	s_and_b32 s88, s33, 7
	s_lshl_b32 s88, s88, 7
	s_ashr_i32 s87, s86, 31
	s_lshl_b64 s[92:93], s[86:87], 11
	s_add_u32 s92, s54, s92
	s_addc_u32 s93, s55, s93
	s_ashr_i32 s89, s88, 31
	s_lshl_b64 s[94:95], s[88:89], 11
	v_readlane_b32 s1, v236, 9
	s_add_u32 s94, s1, s94
	v_readlane_b32 s1, v236, 11
	s_addc_u32 s95, s1, s95
	v_lshl_add_u64 v[76:77], s[92:93], 0, v[66:67]
	global_load_lds_dwordx4 v[76:77], off
	v_lshl_add_u64 v[66:67], s[94:95], 0, v[66:67]
	s_mov_b32 m0, s7
	s_nop 0
	global_load_lds_dwordx4 v[66:67], off
	v_lshl_add_u64 v[66:67], s[92:93], 0, v[68:69]
	s_mov_b32 m0, s38
	s_nop 0
	global_load_lds_dwordx4 v[66:67], off
	v_lshl_add_u64 v[66:67], s[94:95], 0, v[68:69]
	s_mov_b32 m0, s39
	s_nop 0
	global_load_lds_dwordx4 v[66:67], off
	v_lshl_add_u64 v[66:67], s[92:93], 0, v[70:71]
	s_mov_b32 m0, s50
	s_nop 0
	global_load_lds_dwordx4 v[66:67], off
	v_lshl_add_u64 v[66:67], s[94:95], 0, v[70:71]
	s_mov_b32 m0, s51
	s_nop 0
	global_load_lds_dwordx4 v[66:67], off
	v_lshl_add_u64 v[66:67], s[92:93], 0, v[72:73]
	s_mov_b32 m0, s83
	s_nop 0
	global_load_lds_dwordx4 v[66:67], off
	v_lshl_add_u64 v[66:67], s[94:95], 0, v[72:73]
	s_mov_b32 m0, s90
	s_nop 0
	global_load_lds_dwordx4 v[66:67], off
; DI void gemm_out(const Params& p, char* lds) {
;     ...
; #pragma unroll
;         for (int tt = 0; tt < 3; ++tt) {
;             const int row = m0 + wm * 48 + tt * 16 + q;
;             const float* xr = row < NTP ? p.x_p + (size_t)row * DM : p.x_s + (size_t)(row - NTP) * DM;
;             float* o = p.out + (size_t)row * DM;
; #pragma unroll
;             for (int ct = 0; ct < 4; ++ct) { const int col = n0 + wn * 64 + ct * 16 + 4 * g; const float4 xv = xres[tt][ct];
;                 const f32x4 w = {xv.x + acc[ct][tt][0], xv.y + acc[ct][tt][1], xv.z + acc[ct][tt][2], xv.w + acc[ct][tt][3]}; __builtin_nontemporal_store(w, (f32x4*)(o + col)); }
;         }
.Lo_nonext:
	v_readfirstlane_b32 s1, v0
	s_lshr_b32 s1, s1, 6
	s_and_b32 s6, s1, 1
	s_lshr_b32 s4, s1, 1
	s_lshl_b32 s1, s6, 6
	s_add_i32 s1, s1, s82
	s_cmp_lt_u32 s82, 0x4000
	s_cselect_b32 s2, s56, s58
	s_cselect_b32 s3, s57, s59
	s_cselect_b32 s5, 0, 0x4000
	s_sub_i32 s5, s1, s5
	s_lshl_b32 s7, s4, 6
	s_add_i32 s7, s7, s0
	v_and_b32_e32 v164, 31, v0
	v_bfe_u32 v165, v0, 5, 1
	v_lshlrev_b32_e32 v165, 14, v165
	v_add_u32_e32 v166, s7, v164
	v_lshl_add_u32 v166, v166, 2, v165
	s_lshl_b32 s4, s1, 12
	s_lshl_b32 s6, s5, 12
	v_add_u32_e32 v170, s4, v166
	v_add_u32_e32 v169, s6, v166
	global_load_dword v100, v169, s[2:3] nt
	global_load_dword v101, v169, s[2:3] offset:128 nt
	v_add_u32_e32 v169, 0x1000, v169
	global_load_dword v102, v169, s[2:3] nt
	global_load_dword v103, v169, s[2:3] offset:128 nt
	v_add_u32_e32 v169, 0x1000, v169
	global_load_dword v104, v169, s[2:3] nt
	global_load_dword v105, v169, s[2:3] offset:128 nt
	v_add_u32_e32 v169, 0x1000, v169
	global_load_dword v106, v169, s[2:3] nt
	global_load_dword v107, v169, s[2:3] offset:128 nt
	v_add_u32_e32 v169, 0x5000, v169
	global_load_dword v108, v169, s[2:3] nt
	global_load_dword v109, v169, s[2:3] offset:128 nt
	v_add_u32_e32 v169, 0x1000, v169
	global_load_dword v110, v169, s[2:3] nt
	global_load_dword v111, v169, s[2:3] offset:128 nt
	v_add_u32_e32 v169, 0x1000, v169
	global_load_dword v112, v169, s[2:3] nt
	global_load_dword v113, v169, s[2:3] offset:128 nt
	v_add_u32_e32 v169, 0x1000, v169
	global_load_dword v114, v169, s[2:3] nt
	global_load_dword v115, v169, s[2:3] offset:128 nt
	v_add_u32_e32 v169, 0x5000, v169
	global_load_dword v116, v169, s[2:3] nt
	global_load_dword v117, v169, s[2:3] offset:128 nt
	v_add_u32_e32 v169, 0x1000, v169
	global_load_dword v118, v169, s[2:3] nt
	global_load_dword v119, v169, s[2:3] offset:128 nt
	v_add_u32_e32 v169, 0x1000, v169
	global_load_dword v120, v169, s[2:3] nt
	global_load_dword v121, v169, s[2:3] offset:128 nt
	v_add_u32_e32 v169, 0x1000, v169
	global_load_dword v122, v169, s[2:3] nt
	global_load_dword v123, v169, s[2:3] offset:128 nt
	v_add_u32_e32 v169, 0x5000, v169
	global_load_dword v124, v169, s[2:3] nt
	global_load_dword v125, v169, s[2:3] offset:128 nt
	v_add_u32_e32 v169, 0x1000, v169
	global_load_dword v126, v169, s[2:3] nt
	global_load_dword v127, v169, s[2:3] offset:128 nt
	v_add_u32_e32 v169, 0x1000, v169
	global_load_dword v128, v169, s[2:3] nt
	global_load_dword v129, v169, s[2:3] offset:128 nt
	v_add_u32_e32 v169, 0x1000, v169
	global_load_dword v130, v169, s[2:3] nt
	global_load_dword v131, v169, s[2:3] offset:128 nt
	v_add_u32_e32 v169, 0x5000, v169
	global_load_dword v132, v169, s[2:3] nt
	global_load_dword v133, v169, s[2:3] offset:128 nt
	v_add_u32_e32 v169, 0x1000, v169
	global_load_dword v134, v169, s[2:3] nt
	global_load_dword v135, v169, s[2:3] offset:128 nt
	v_add_u32_e32 v169, 0x1000, v169
	global_load_dword v136, v169, s[2:3] nt
	global_load_dword v137, v169, s[2:3] offset:128 nt
	v_add_u32_e32 v169, 0x1000, v169
	global_load_dword v138, v169, s[2:3] nt
	global_load_dword v139, v169, s[2:3] offset:128 nt
	v_add_u32_e32 v169, 0x5000, v169
	global_load_dword v140, v169, s[2:3] nt
	global_load_dword v141, v169, s[2:3] offset:128 nt
	v_add_u32_e32 v169, 0x1000, v169
	global_load_dword v142, v169, s[2:3] nt
	global_load_dword v143, v169, s[2:3] offset:128 nt
	v_add_u32_e32 v169, 0x1000, v169
	global_load_dword v144, v169, s[2:3] nt
	global_load_dword v145, v169, s[2:3] offset:128 nt
	v_add_u32_e32 v169, 0x1000, v169
	global_load_dword v146, v169, s[2:3] nt
	global_load_dword v147, v169, s[2:3] offset:128 nt
	v_add_u32_e32 v169, 0x5000, v169
	global_load_dword v148, v169, s[2:3] nt
	global_load_dword v149, v169, s[2:3] offset:128 nt
	v_add_u32_e32 v169, 0x1000, v169
	global_load_dword v150, v169, s[2:3] nt
	global_load_dword v151, v169, s[2:3] offset:128 nt
	v_add_u32_e32 v169, 0x1000, v169
	global_load_dword v152, v169, s[2:3] nt
	global_load_dword v153, v169, s[2:3] offset:128 nt
	v_add_u32_e32 v169, 0x1000, v169
	global_load_dword v154, v169, s[2:3] nt
	global_load_dword v155, v169, s[2:3] offset:128 nt
	v_add_u32_e32 v169, 0x5000, v169
	global_load_dword v156, v169, s[2:3] nt
	global_load_dword v157, v169, s[2:3] offset:128 nt
	v_add_u32_e32 v169, 0x1000, v169
	global_load_dword v158, v169, s[2:3] nt
	global_load_dword v159, v169, s[2:3] offset:128 nt
	v_add_u32_e32 v169, 0x1000, v169
	global_load_dword v160, v169, s[2:3] nt
	global_load_dword v161, v169, s[2:3] offset:128 nt
	v_add_u32_e32 v169, 0x1000, v169
	global_load_dword v162, v169, s[2:3] nt
	global_load_dword v163, v169, s[2:3] offset:128 nt
	s_waitcnt vmcnt(63)
	v_add_f32_e32 v34, v34, v100
	global_store_dword v170, v34, s[52:53] nt
	s_waitcnt vmcnt(63)
	v_add_f32_e32 v50, v50, v101
	global_store_dword v170, v50, s[52:53] offset:128 nt
	v_add_u32_e32 v170, 0x1000, v170
	s_waitcnt vmcnt(63)
	v_add_f32_e32 v35, v35, v102
	global_store_dword v170, v35, s[52:53] nt
	s_waitcnt vmcnt(63)
	v_add_f32_e32 v51, v51, v103
	global_store_dword v170, v51, s[52:53] offset:128 nt
	v_add_u32_e32 v170, 0x1000, v170
	s_waitcnt vmcnt(63)
	v_add_f32_e32 v36, v36, v104
	global_store_dword v170, v36, s[52:53] nt
	s_waitcnt vmcnt(63)
	v_add_f32_e32 v52, v52, v105
	global_store_dword v170, v52, s[52:53] offset:128 nt
	v_add_u32_e32 v170, 0x1000, v170
	s_waitcnt vmcnt(63)
	v_add_f32_e32 v37, v37, v106
	global_store_dword v170, v37, s[52:53] nt
	s_waitcnt vmcnt(63)
	v_add_f32_e32 v53, v53, v107
	global_store_dword v170, v53, s[52:53] offset:128 nt
	v_add_u32_e32 v170, 0x5000, v170
	s_waitcnt vmcnt(63)
	v_add_f32_e32 v38, v38, v108
	global_store_dword v170, v38, s[52:53] nt
	s_waitcnt vmcnt(63)
; DI void gemm_out(const Params& p, char* lds) {
;     ...
;     for (int tile = vb; tile < ntile; tile += gridDim.x) {
;     ...
; #pragma unroll
;         for (int tt = 0; tt < 3; ++tt) {
;             const int row = m0 + wm * 48 + tt * 16 + q;
;             const float* xr = row < NTP ? p.x_p + (size_t)row * DM : p.x_s + (size_t)(row - NTP) * DM;
;             float* o = p.out + (size_t)row * DM;
; #pragma unroll
;             for (int ct = 0; ct < 4; ++ct) { const int col = n0 + wn * 64 + ct * 16 + 4 * g; const float4 xv = xres[tt][ct];
;                 const f32x4 w = {xv.x + acc[ct][tt][0], xv.y + acc[ct][tt][1], xv.z + acc[ct][tt][2], xv.w + acc[ct][tt][3]}; __builtin_nontemporal_store(w, (f32x4*)(o + col)); }
;         }
	v_add_f32_e32 v54, v54, v109
	global_store_dword v170, v54, s[52:53] offset:128 nt
	v_add_u32_e32 v170, 0x1000, v170
	s_waitcnt vmcnt(63)
	v_add_f32_e32 v39, v39, v110
	global_store_dword v170, v39, s[52:53] nt
	s_waitcnt vmcnt(63)
	v_add_f32_e32 v55, v55, v111
	global_store_dword v170, v55, s[52:53] offset:128 nt
	v_add_u32_e32 v170, 0x1000, v170
	s_waitcnt vmcnt(63)
	v_add_f32_e32 v40, v40, v112
	global_store_dword v170, v40, s[52:53] nt
	s_waitcnt vmcnt(63)
	v_add_f32_e32 v56, v56, v113
	global_store_dword v170, v56, s[52:53] offset:128 nt
	v_add_u32_e32 v170, 0x1000, v170
	s_waitcnt vmcnt(63)
	v_add_f32_e32 v41, v41, v114
	global_store_dword v170, v41, s[52:53] nt
	s_waitcnt vmcnt(63)
	v_add_f32_e32 v57, v57, v115
	global_store_dword v170, v57, s[52:53] offset:128 nt
	v_add_u32_e32 v170, 0x5000, v170
	s_waitcnt vmcnt(63)
	v_add_f32_e32 v42, v42, v116
	global_store_dword v170, v42, s[52:53] nt
	s_waitcnt vmcnt(63)
	v_add_f32_e32 v58, v58, v117
	global_store_dword v170, v58, s[52:53] offset:128 nt
	v_add_u32_e32 v170, 0x1000, v170
	s_waitcnt vmcnt(63)
	v_add_f32_e32 v43, v43, v118
	global_store_dword v170, v43, s[52:53] nt
	s_waitcnt vmcnt(63)
	v_add_f32_e32 v59, v59, v119
	global_store_dword v170, v59, s[52:53] offset:128 nt
	v_add_u32_e32 v170, 0x1000, v170
	s_waitcnt vmcnt(63)
	v_add_f32_e32 v44, v44, v120
	global_store_dword v170, v44, s[52:53] nt
	s_waitcnt vmcnt(63)
	v_add_f32_e32 v60, v60, v121
	global_store_dword v170, v60, s[52:53] offset:128 nt
	v_add_u32_e32 v170, 0x1000, v170
	s_waitcnt vmcnt(63)
	v_add_f32_e32 v45, v45, v122
	global_store_dword v170, v45, s[52:53] nt
	s_waitcnt vmcnt(63)
	v_add_f32_e32 v61, v61, v123
	global_store_dword v170, v61, s[52:53] offset:128 nt
	v_add_u32_e32 v170, 0x5000, v170
	s_waitcnt vmcnt(63)
	v_add_f32_e32 v46, v46, v124
	global_store_dword v170, v46, s[52:53] nt
	s_waitcnt vmcnt(63)
	v_add_f32_e32 v62, v62, v125
	global_store_dword v170, v62, s[52:53] offset:128 nt
	v_add_u32_e32 v170, 0x1000, v170
	s_waitcnt vmcnt(63)
	v_add_f32_e32 v47, v47, v126
	global_store_dword v170, v47, s[52:53] nt
	s_waitcnt vmcnt(63)
	v_add_f32_e32 v63, v63, v127
	global_store_dword v170, v63, s[52:53] offset:128 nt
	v_add_u32_e32 v170, 0x1000, v170
	s_waitcnt vmcnt(63)
	v_add_f32_e32 v48, v48, v128
	global_store_dword v170, v48, s[52:53] nt
	s_waitcnt vmcnt(63)
	v_add_f32_e32 v64, v64, v129
	global_store_dword v170, v64, s[52:53] offset:128 nt
	v_add_u32_e32 v170, 0x1000, v170
	s_waitcnt vmcnt(63)
	v_add_f32_e32 v49, v49, v130
	global_store_dword v170, v49, s[52:53] nt
	s_waitcnt vmcnt(63)
	v_add_f32_e32 v65, v65, v131
	global_store_dword v170, v65, s[52:53] offset:128 nt
	v_add_u32_e32 v170, 0x5000, v170
	s_waitcnt vmcnt(63)
	v_add_f32_e32 v18, v18, v132
	global_store_dword v170, v18, s[52:53] nt
	s_waitcnt vmcnt(63)
	v_add_f32_e32 v2, v2, v133
	global_store_dword v170, v2, s[52:53] offset:128 nt
	v_add_u32_e32 v170, 0x1000, v170
	s_waitcnt vmcnt(63)
	v_add_f32_e32 v19, v19, v134
	global_store_dword v170, v19, s[52:53] nt
	s_waitcnt vmcnt(63)
	v_add_f32_e32 v3, v3, v135
	global_store_dword v170, v3, s[52:53] offset:128 nt
	v_add_u32_e32 v170, 0x1000, v170
	s_waitcnt vmcnt(63)
	v_add_f32_e32 v20, v20, v136
	global_store_dword v170, v20, s[52:53] nt
	s_waitcnt vmcnt(63)
	v_add_f32_e32 v4, v4, v137
	global_store_dword v170, v4, s[52:53] offset:128 nt
	v_add_u32_e32 v170, 0x1000, v170
	s_waitcnt vmcnt(63)
	v_add_f32_e32 v21, v21, v138
	global_store_dword v170, v21, s[52:53] nt
	s_waitcnt vmcnt(63)
	v_add_f32_e32 v5, v5, v139
	global_store_dword v170, v5, s[52:53] offset:128 nt
	v_add_u32_e32 v170, 0x5000, v170
	s_waitcnt vmcnt(63)
	v_add_f32_e32 v22, v22, v140
	global_store_dword v170, v22, s[52:53] nt
	s_waitcnt vmcnt(63)
	v_add_f32_e32 v6, v6, v141
	global_store_dword v170, v6, s[52:53] offset:128 nt
	v_add_u32_e32 v170, 0x1000, v170
	s_waitcnt vmcnt(63)
	v_add_f32_e32 v23, v23, v142
	global_store_dword v170, v23, s[52:53] nt
	s_waitcnt vmcnt(63)
	v_add_f32_e32 v7, v7, v143
	global_store_dword v170, v7, s[52:53] offset:128 nt
	v_add_u32_e32 v170, 0x1000, v170
	s_waitcnt vmcnt(63)
	v_add_f32_e32 v24, v24, v144
	global_store_dword v170, v24, s[52:53] nt
	s_waitcnt vmcnt(63)
	v_add_f32_e32 v8, v8, v145
	global_store_dword v170, v8, s[52:53] offset:128 nt
	v_add_u32_e32 v170, 0x1000, v170
	s_waitcnt vmcnt(63)
	v_add_f32_e32 v25, v25, v146
	global_store_dword v170, v25, s[52:53] nt
	s_waitcnt vmcnt(63)
	v_add_f32_e32 v9, v9, v147
	global_store_dword v170, v9, s[52:53] offset:128 nt
	v_add_u32_e32 v170, 0x5000, v170
	s_waitcnt vmcnt(63)
	v_add_f32_e32 v26, v26, v148
	global_store_dword v170, v26, s[52:53] nt
	s_waitcnt vmcnt(63)
	v_add_f32_e32 v10, v10, v149
	global_store_dword v170, v10, s[52:53] offset:128 nt
	v_add_u32_e32 v170, 0x1000, v170
	s_waitcnt vmcnt(63)
	v_add_f32_e32 v27, v27, v150
	global_store_dword v170, v27, s[52:53] nt
	s_waitcnt vmcnt(63)
	v_add_f32_e32 v11, v11, v151
	global_store_dword v170, v11, s[52:53] offset:128 nt
	v_add_u32_e32 v170, 0x1000, v170
	s_waitcnt vmcnt(63)
	v_add_f32_e32 v28, v28, v152
	global_store_dword v170, v28, s[52:53] nt
	s_waitcnt vmcnt(63)
	v_add_f32_e32 v12, v12, v153
	global_store_dword v170, v12, s[52:53] offset:128 nt
	v_add_u32_e32 v170, 0x1000, v170
	s_waitcnt vmcnt(63)
	v_add_f32_e32 v29, v29, v154
	global_store_dword v170, v29, s[52:53] nt
	s_waitcnt vmcnt(63)
	v_add_f32_e32 v13, v13, v155
	global_store_dword v170, v13, s[52:53] offset:128 nt
	v_add_u32_e32 v170, 0x5000, v170
	s_waitcnt vmcnt(63)
	v_add_f32_e32 v30, v30, v156
	global_store_dword v170, v30, s[52:53] nt
	s_waitcnt vmcnt(63)
	v_add_f32_e32 v14, v14, v157
	global_store_dword v170, v14, s[52:53] offset:128 nt
	v_add_u32_e32 v170, 0x1000, v170
	s_waitcnt vmcnt(63)
	v_add_f32_e32 v31, v31, v158
	global_store_dword v170, v31, s[52:53] nt
	s_waitcnt vmcnt(63)
	v_add_f32_e32 v15, v15, v159
	global_store_dword v170, v15, s[52:53] offset:128 nt
	v_add_u32_e32 v170, 0x1000, v170
	s_waitcnt vmcnt(63)
	v_add_f32_e32 v32, v32, v160
	global_store_dword v170, v32, s[52:53] nt
	s_waitcnt vmcnt(63)
	v_add_f32_e32 v16, v16, v161
	global_store_dword v170, v16, s[52:53] offset:128 nt
	v_add_u32_e32 v170, 0x1000, v170
	s_waitcnt vmcnt(63)
	v_add_f32_e32 v33, v33, v162
	global_store_dword v170, v33, s[52:53] nt
	s_waitcnt vmcnt(63)
	v_add_f32_e32 v17, v17, v163
	global_store_dword v170, v17, s[52:53] offset:128 nt
	v_readlane_b32 s95, v236, 8
	s_cmpk_lt_i32 s33, 0x420
	s_mov_b32 s0, s88
	s_mov_b32 s82, s86
	s_cbranch_scc1 .Lo_tile
